# experiment: nt stores also for the bf16 U outputs of the in-proj epilogue
# baseline (speedup 1.0000x reference)
.LBB0_169:
	v_cvt_pk_bf16_f32 v140, v134, v135
	v_cvt_pk_bf16_f32 v141, v138, v139
	v_cvt_pk_bf16_f32 v142, v132, v133
	v_mov_b64_e32 v[132:133], s[10:11]
	v_mad_i64_i32 v[132:133], s[0:1], v164, s8, v[132:133]
	v_ashrrev_i32_e32 v167, 31, v166
	v_cndmask_b32_e64 v134, 0, 1, s[6:7]
	v_lshl_add_u64 v[132:133], v[166:167], 1, v[132:133]
	v_cmp_ne_u32_e64 s[4:5], 1, v134
	s_andn2_b64 vcc, exec, s[6:7]
	s_mov_b64 s[0:1], -1
	v_cvt_pk_bf16_f32 v143, v136, v137
	global_store_dwordx4 v[132:133], v[140:143], off nt
	s_cbranch_vccnz .LBB0_176
	s_mov_b64 s[34:35], -1
	s_mov_b64 s[0:1], 0
	s_cmp_lt_i32 s23, 4
	s_mov_b64 s[6:7], 0
	s_cbranch_scc0 .LBB0_377
	s_and_b64 vcc, exec, s[34:35]
	s_cbranch_vccnz .LBB0_380

.LBB0_182:
	s_and_b64 vcc, exec, s[4:5]
	s_mov_b64 s[0:1], -1
	v_cvt_pk_bf16_f32 v168, v136, v137
	v_cvt_pk_bf16_f32 v169, v140, v141
	v_cvt_pk_bf16_f32 v170, v134, v135
	v_cvt_pk_bf16_f32 v171, v138, v139
	global_store_dwordx4 v[132:133], v[168:171], off offset:256 nt
	s_cbranch_vccnz .LBB0_189
	s_mov_b64 s[34:35], -1
	s_mov_b64 s[0:1], 0
	s_cmp_lt_i32 s23, 4
	s_mov_b64 s[6:7], 0
	s_cbranch_scc0 .LBB0_386
	s_and_b64 vcc, exec, s[34:35]
	s_cbranch_vccnz .LBB0_389

.LBB0_195:
	v_cvt_pk_bf16_f32 v168, v136, v137
	v_cvt_pk_bf16_f32 v169, v140, v141
	v_cvt_pk_bf16_f32 v170, v134, v135
	v_mov_b64_e32 v[134:135], s[10:11]
	v_mad_i64_i32 v[134:135], s[0:1], v132, s8, v[134:135]
	v_lshl_add_u64 v[134:135], v[166:167], 1, v[134:135]
	s_and_b64 vcc, exec, s[4:5]
	s_mov_b64 s[0:1], -1
	v_cvt_pk_bf16_f32 v171, v138, v139
	global_store_dwordx4 v[134:135], v[168:171], off nt
	s_cbranch_vccnz .LBB0_202
	s_mov_b64 s[34:35], -1
	s_mov_b64 s[0:1], 0
	s_cmp_lt_i32 s23, 4
	s_mov_b64 s[6:7], 0
	s_cbranch_scc0 .LBB0_395
	s_and_b64 vcc, exec, s[34:35]
	s_cbranch_vccnz .LBB0_398

.LBB0_208:
	s_and_b64 vcc, exec, s[4:5]
	s_mov_b64 s[0:1], -1
	v_cvt_pk_bf16_f32 v130, v138, v139
	v_cvt_pk_bf16_f32 v131, v142, v143
	v_cvt_pk_bf16_f32 v132, v136, v137
	v_cvt_pk_bf16_f32 v133, v140, v141
	global_store_dwordx4 v[134:135], v[130:133], off offset:256 nt
	s_cbranch_vccnz .LBB0_215
	s_mov_b64 s[34:35], -1
	s_mov_b64 s[0:1], 0
	s_cmp_lt_i32 s23, 4
	s_mov_b64 s[6:7], 0
	s_cbranch_scc0 .LBB0_404
	s_and_b64 vcc, exec, s[34:35]
	s_cbranch_vccnz .LBB0_407

.LBB0_351:
	v_cvt_pk_bf16_f32 v168, v136, v137
	v_cvt_pk_bf16_f32 v169, v140, v141
	v_cvt_pk_bf16_f32 v170, v134, v135
	v_mov_b64_e32 v[134:135], s[10:11]
	v_mad_i64_i32 v[134:135], s[0:1], v130, s8, v[134:135]
	v_lshl_add_u64 v[134:135], v[166:167], 1, v[134:135]
	s_and_b64 vcc, exec, s[4:5]
	s_mov_b64 s[0:1], -1
	v_cvt_pk_bf16_f32 v171, v138, v139
	global_store_dwordx4 v[134:135], v[168:171], off nt
	s_cbranch_vccnz .LBB0_358
	s_mov_b64 s[6:7], -1
	s_mov_b64 s[0:1], 0
	s_cmp_lt_i32 s23, 4
	s_mov_b64 s[4:5], 0
	s_cbranch_scc0 .LBB0_503
	s_and_b64 vcc, exec, s[6:7]
	s_cbranch_vccnz .LBB0_506

.LBB0_364:
	v_cvt_pk_bf16_f32 v130, v140, v141
	v_cvt_pk_bf16_f32 v131, v142, v143
	v_cvt_pk_bf16_f32 v132, v136, v137
	v_cvt_pk_bf16_f32 v133, v138, v139
	global_store_dwordx4 v[134:135], v[130:133], off offset:256 nt
	s_branch .LBB0_155
.LBB0_365:
	v_mov_b32_e32 v167, v155
	v_readlane_b32 s52, v254, 11
	v_lshlrev_b64 v[168:169], 2, v[166:167]
	v_readlane_b32 s62, v254, 21
	v_readlane_b32 s63, v254, 22
	v_mul_f32_e32 v126, 0xbfb8aa3b, v126
	v_exp_f32_e32 v126, v126
	v_lshl_add_u64 v[186:187], s[62:63], 0, v[168:169]
	global_load_dwordx4 v[130:133], v[186:187], off offset:-4080
	global_load_dwordx4 v[138:141], v[186:187], off offset:-4096
	global_load_dwordx4 v[134:137], v[186:187], off offset:16
	global_load_dwordx4 v[142:145], v[186:187], off
	v_mul_f32_e32 v122, 0xbfb8aa3b, v122
	v_add_f32_e32 v126, 1.0, v126
	v_exp_f32_e32 v122, v122
	v_mul_f32_e32 v127, 0xbfb8aa3b, v127
	v_exp_f32_e32 v127, v127
	v_mul_f32_e32 v123, 0xbfb8aa3b, v123
	v_add_f32_e32 v122, 1.0, v122
	v_rcp_f32_e32 v184, v122
	v_add_f32_e32 v127, 1.0, v127
	v_exp_f32_e32 v123, v123
	v_mul_f32_e32 v128, 0xbfb8aa3b, v128
	v_exp_f32_e32 v128, v128
	v_mul_f32_e32 v124, 0xbfb8aa3b, v124
	v_add_f32_e32 v123, 1.0, v123
	v_rcp_f32_e32 v182, v123
	v_add_f32_e32 v128, 1.0, v128
	v_exp_f32_e32 v124, v124
	v_mul_f32_e32 v129, 0xbfb8aa3b, v129
	v_exp_f32_e32 v129, v129
	v_mul_f32_e32 v125, 0xbfb8aa3b, v125
	v_add_f32_e32 v124, 1.0, v124
	v_rcp_f32_e32 v180, v124
	v_add_f32_e32 v129, 1.0, v129
	v_rcp_f32_e32 v176, v129
	v_exp_f32_e32 v125, v125
	v_mul_f32_e32 v118, 0xbfb8aa3b, v118
	v_exp_f32_e32 v118, v118
	v_mul_f32_e32 v114, 0xbfb8aa3b, v114
	v_add_f32_e32 v125, 1.0, v125
	v_rcp_f32_e32 v178, v125
	v_add_f32_e32 v118, 1.0, v118
	v_rcp_f32_e32 v188, v118
	v_exp_f32_e32 v114, v114
	v_lshlrev_b64 v[194:195], 12, v[164:165]
	v_lshl_add_u64 v[194:195], s[12:13], 0, v[194:195]
	v_lshl_add_u64 v[212:213], v[194:195], 0, v[168:169]
	v_add_f32_e32 v114, 1.0, v114
	v_mov_b64_e32 v[208:209], s[10:11]
	v_lshlrev_b64 v[210:211], 1, v[166:167]
	v_mul_f32_e32 v119, 0xbfb8aa3b, v119
	v_exp_f32_e32 v119, v119
	v_mul_f32_e32 v115, 0xbfb8aa3b, v115
	v_exp_f32_e32 v115, v115
	v_mul_f32_e32 v120, 0xbfb8aa3b, v120
	v_add_f32_e32 v119, 1.0, v119
	v_exp_f32_e32 v120, v120
	v_add_f32_e32 v115, 1.0, v115
	v_mul_f32_e32 v116, 0xbfb8aa3b, v116
	v_exp_f32_e32 v116, v116
	v_add_f32_e32 v120, 1.0, v120
	v_mul_f32_e32 v121, 0xbfb8aa3b, v121
	v_exp_f32_e32 v121, v121
	v_add_f32_e32 v116, 1.0, v116
	v_mul_f32_e32 v117, 0xbfb8aa3b, v117
	v_exp_f32_e32 v117, v117
	v_add_f32_e32 v121, 1.0, v121
	v_mul_f32_e32 v110, 0xbfb8aa3b, v110
	v_exp_f32_e32 v110, v110
	v_add_f32_e32 v117, 1.0, v117
	v_mul_f32_e32 v106, 0xbfb8aa3b, v106
	v_exp_f32_e32 v106, v106
	v_add_f32_e32 v110, 1.0, v110
	v_mul_f32_e32 v111, 0xbfb8aa3b, v111
	v_exp_f32_e32 v111, v111
	v_add_f32_e32 v106, 1.0, v106
	v_mul_f32_e32 v107, 0xbfb8aa3b, v107
	v_exp_f32_e32 v107, v107
	v_add_f32_e32 v111, 1.0, v111
	v_mul_f32_e32 v112, 0xbfb8aa3b, v112
	v_exp_f32_e32 v112, v112
	v_add_f32_e32 v107, 1.0, v107
	v_mul_f32_e32 v108, 0xbfb8aa3b, v108
	v_exp_f32_e32 v108, v108
	v_add_f32_e32 v112, 1.0, v112
	v_mul_f32_e32 v113, 0xbfb8aa3b, v113
	v_exp_f32_e32 v113, v113
	v_add_f32_e32 v108, 1.0, v108
	v_mul_f32_e32 v109, 0xbfb8aa3b, v109
	s_waitcnt vmcnt(0)
	v_sub_f32_e32 v130, v134, v130
	v_sub_f32_e32 v138, v142, v138
	v_mul_f32_e32 v142, 0x3fb8aa3b, v138
	v_fma_f32 v154, v138, s9, -v142
	v_rndne_f32_e32 v170, v142
	v_fmac_f32_e32 v154, 0x32a5705f, v138
	v_sub_f32_e32 v142, v142, v170
	v_add_f32_e32 v142, v142, v154
	v_exp_f32_e32 v142, v142
	v_cvt_i32_f32_e32 v154, v170
	v_cmp_ngt_f32_e32 vcc, s95, v138
	v_mul_f32_e32 v134, 0x3fb8aa3b, v130
	v_add_f32_e32 v113, 1.0, v113
	v_ldexp_f32 v142, v142, v154
	v_cndmask_b32_e32 v142, 0, v142, vcc
	v_cmp_nlt_f32_e32 vcc, s85, v138
	v_exp_f32_e32 v109, v109
	v_mul_f32_e32 v102, 0xbfb8aa3b, v102
	v_cndmask_b32_e32 v138, v223, v142, vcc
	v_add_f32_e32 v138, 1.0, v138
	v_div_scale_f32 v142, s[0:1], v138, v138, 1.0
	v_rcp_f32_e32 v154, v142
	v_add_f32_e32 v109, 1.0, v109
	v_exp_f32_e32 v102, v102
	v_mul_f32_e32 v98, 0xbfb8aa3b, v98
	v_fma_f32 v170, -v142, v154, 1.0
	v_fmac_f32_e32 v154, v170, v154
	v_div_scale_f32 v170, vcc, 1.0, v138, 1.0
	v_mul_f32_e32 v171, v170, v154
	v_fma_f32 v172, -v142, v171, v170
	v_fmac_f32_e32 v171, v172, v154
	v_fma_f32 v142, -v142, v171, v170
	v_div_fmas_f32 v142, v142, v154, v171
	v_div_fixup_f32 v171, v142, v138, 1.0
	v_sub_f32_e32 v138, v143, v139
	v_mul_f32_e32 v139, 0x3fb8aa3b, v138
	v_fma_f32 v142, v138, s9, -v139
	v_rndne_f32_e32 v143, v139
	v_fmac_f32_e32 v142, 0x32a5705f, v138
	v_sub_f32_e32 v139, v139, v143
	v_add_f32_e32 v139, v139, v142
	v_exp_f32_e32 v139, v139
	v_cvt_i32_f32_e32 v142, v143
	v_cmp_ngt_f32_e32 vcc, s95, v138
	v_add_f32_e32 v102, 1.0, v102
	v_exp_f32_e32 v98, v98
	v_ldexp_f32 v139, v139, v142
	v_cndmask_b32_e32 v139, 0, v139, vcc
	v_cmp_nlt_f32_e32 vcc, s85, v138
	v_add_f32_e32 v98, 1.0, v98
	v_mul_f32_e32 v103, 0xbfb8aa3b, v103
	v_cndmask_b32_e32 v138, v223, v139, vcc
	v_add_f32_e32 v138, 1.0, v138
	v_div_scale_f32 v139, s[0:1], v138, v138, 1.0
	v_rcp_f32_e32 v142, v139
	v_exp_f32_e32 v103, v103
	v_mul_f32_e32 v99, 0xbfb8aa3b, v99
	v_exp_f32_e32 v99, v99
	v_fma_f32 v143, -v139, v142, 1.0
	v_fmac_f32_e32 v142, v143, v142
	v_div_scale_f32 v143, vcc, 1.0, v138, 1.0
	v_mul_f32_e32 v154, v143, v142
	v_fma_f32 v170, -v139, v154, v143
	v_fmac_f32_e32 v154, v170, v142
	v_fma_f32 v139, -v139, v154, v143
	v_div_fmas_f32 v139, v139, v142, v154
	v_div_fixup_f32 v173, v139, v138, 1.0
	v_sub_f32_e32 v138, v144, v140
	v_mul_f32_e32 v139, 0x3fb8aa3b, v138
	v_fma_f32 v140, v138, s9, -v139
	v_rndne_f32_e32 v142, v139
	v_fmac_f32_e32 v140, 0x32a5705f, v138
	v_sub_f32_e32 v139, v139, v142
	v_add_f32_e32 v139, v139, v140
	v_exp_f32_e32 v139, v139
	v_cvt_i32_f32_e32 v140, v142
	v_cmp_ngt_f32_e32 vcc, s95, v138
	v_add_f32_e32 v103, 1.0, v103
	v_add_f32_e32 v99, 1.0, v99
	v_ldexp_f32 v139, v139, v140
	v_cndmask_b32_e32 v139, 0, v139, vcc
	v_cmp_nlt_f32_e32 vcc, s85, v138
	v_mul_f32_e32 v104, 0xbfb8aa3b, v104
	v_exp_f32_e32 v104, v104
	v_cndmask_b32_e32 v138, v223, v139, vcc
	v_add_f32_e32 v138, 1.0, v138
	v_div_scale_f32 v139, s[0:1], v138, v138, 1.0
	v_rcp_f32_e32 v140, v139
	v_mul_f32_e32 v100, 0xbfb8aa3b, v100
	v_add_f32_e32 v104, 1.0, v104
	v_exp_f32_e32 v100, v100
	v_fma_f32 v142, -v139, v140, 1.0
	v_fmac_f32_e32 v140, v142, v140
	v_div_scale_f32 v142, vcc, 1.0, v138, 1.0
	v_mul_f32_e32 v143, v142, v140
	v_fma_f32 v144, -v139, v143, v142
	v_fmac_f32_e32 v143, v144, v140
	v_fma_f32 v139, -v139, v143, v142
	v_div_fmas_f32 v139, v139, v140, v143
	v_div_fixup_f32 v175, v139, v138, 1.0
	v_sub_f32_e32 v138, v145, v141
	v_mul_f32_e32 v139, 0x3fb8aa3b, v138
	v_fma_f32 v140, v138, s9, -v139
	v_rndne_f32_e32 v141, v139
	v_fmac_f32_e32 v140, 0x32a5705f, v138
	v_sub_f32_e32 v139, v139, v141
	v_add_f32_e32 v139, v139, v140
	v_exp_f32_e32 v139, v139
	v_cvt_i32_f32_e32 v140, v141
	v_cmp_ngt_f32_e32 vcc, s95, v138
	v_add_f32_e32 v100, 1.0, v100
	v_mul_f32_e32 v105, 0xbfb8aa3b, v105
	v_ldexp_f32 v139, v139, v140
	v_cndmask_b32_e32 v139, 0, v139, vcc
	v_cmp_nlt_f32_e32 vcc, s85, v138
	v_exp_f32_e32 v105, v105
	v_mul_f32_e32 v101, 0xbfb8aa3b, v101
	v_cndmask_b32_e32 v138, v223, v139, vcc
	v_add_f32_e32 v138, 1.0, v138
	v_div_scale_f32 v139, s[0:1], v138, v138, 1.0
	v_rcp_f32_e32 v140, v139
	v_add_f32_e32 v105, 1.0, v105
	v_exp_f32_e32 v101, v101
	v_mul_f32_e32 v94, 0xbfb8aa3b, v94
	v_fma_f32 v141, -v139, v140, 1.0
	v_fmac_f32_e32 v140, v141, v140
	v_div_scale_f32 v141, vcc, 1.0, v138, 1.0
	v_mul_f32_e32 v142, v141, v140
	v_fma_f32 v143, -v139, v142, v141
	v_fmac_f32_e32 v142, v143, v140
	v_fma_f32 v139, -v139, v142, v141
	v_div_fmas_f32 v139, v139, v140, v142
	v_div_fixup_f32 v177, v139, v138, 1.0
	v_fma_f32 v138, v130, s9, -v134
	v_rndne_f32_e32 v139, v134
	v_fmac_f32_e32 v138, 0x32a5705f, v130
	v_sub_f32_e32 v134, v134, v139
	v_add_f32_e32 v134, v134, v138
	v_exp_f32_e32 v134, v134
	v_cvt_i32_f32_e32 v138, v139
	v_cmp_ngt_f32_e32 vcc, s95, v130
	v_add_f32_e32 v101, 1.0, v101
	v_exp_f32_e32 v94, v94
	v_ldexp_f32 v134, v134, v138
	v_cndmask_b32_e32 v134, 0, v134, vcc
	v_cmp_nlt_f32_e32 vcc, s85, v130
	v_mul_f32_e32 v90, 0xbfb8aa3b, v90
	v_add_f32_e32 v94, 1.0, v94
	v_cndmask_b32_e32 v130, v223, v134, vcc
	v_add_f32_e32 v130, 1.0, v130
	v_div_scale_f32 v134, s[0:1], v130, v130, 1.0
	v_rcp_f32_e32 v138, v134
	v_exp_f32_e32 v90, v90
	v_mul_f32_e32 v95, 0xbfb8aa3b, v95
	v_exp_f32_e32 v95, v95
	v_fma_f32 v139, -v134, v138, 1.0
	v_fmac_f32_e32 v138, v139, v138
	v_div_scale_f32 v139, vcc, 1.0, v130, 1.0
	v_mul_f32_e32 v140, v139, v138
	v_fma_f32 v141, -v134, v140, v139
	v_fmac_f32_e32 v140, v141, v138
	v_fma_f32 v134, -v134, v140, v139
	v_div_fmas_f32 v134, v134, v138, v140
	v_div_fixup_f32 v185, v134, v130, 1.0
	v_sub_f32_e32 v130, v135, v131
	v_mul_f32_e32 v131, 0x3fb8aa3b, v130
	v_fma_f32 v134, v130, s9, -v131
	v_rndne_f32_e32 v135, v131
	v_fmac_f32_e32 v134, 0x32a5705f, v130
	v_sub_f32_e32 v131, v131, v135
	v_add_f32_e32 v131, v131, v134
	v_exp_f32_e32 v131, v131
	v_cvt_i32_f32_e32 v134, v135
	v_cmp_ngt_f32_e32 vcc, s95, v130
	v_pk_add_f32 v[206:207], v[184:185], 1.0 op_sel_hi:[1,0] neg_lo:[1,0] neg_hi:[1,0]
	v_add_f32_e32 v90, 1.0, v90
	v_ldexp_f32 v131, v131, v134
	v_cndmask_b32_e32 v131, 0, v131, vcc
	v_cmp_nlt_f32_e32 vcc, s85, v130
	v_mul_f32_e32 v91, 0xbfb8aa3b, v91
	v_add_f32_e32 v95, 1.0, v95
	v_cndmask_b32_e32 v130, v223, v131, vcc
	v_add_f32_e32 v130, 1.0, v130
	v_div_scale_f32 v131, s[0:1], v130, v130, 1.0
	v_rcp_f32_e32 v134, v131
	v_exp_f32_e32 v91, v91
	v_mul_f32_e32 v96, 0xbfb8aa3b, v96
	v_exp_f32_e32 v96, v96
	v_fma_f32 v135, -v131, v134, 1.0
	v_fmac_f32_e32 v134, v135, v134
	v_div_scale_f32 v135, vcc, 1.0, v130, 1.0
	v_mul_f32_e32 v138, v135, v134
	v_fma_f32 v139, -v131, v138, v135
	v_fmac_f32_e32 v138, v139, v134
	v_fma_f32 v131, -v131, v138, v135
	v_div_fmas_f32 v131, v131, v134, v138
	v_div_fixup_f32 v183, v131, v130, 1.0
	v_sub_f32_e32 v130, v136, v132
	v_mul_f32_e32 v131, 0x3fb8aa3b, v130
	v_fma_f32 v132, v130, s9, -v131
	v_rndne_f32_e32 v134, v131
	v_fmac_f32_e32 v132, 0x32a5705f, v130
	v_sub_f32_e32 v131, v131, v134
	v_add_f32_e32 v131, v131, v132
	v_exp_f32_e32 v131, v131
	v_cvt_i32_f32_e32 v132, v134
	v_cmp_ngt_f32_e32 vcc, s95, v130
	v_pk_add_f32 v[204:205], v[182:183], 1.0 op_sel_hi:[1,0] neg_lo:[1,0] neg_hi:[1,0]
	v_add_f32_e32 v91, 1.0, v91
	v_ldexp_f32 v131, v131, v132
	v_cndmask_b32_e32 v131, 0, v131, vcc
	v_cmp_nlt_f32_e32 vcc, s85, v130
	v_mul_f32_e32 v92, 0xbfb8aa3b, v92
	v_add_f32_e32 v96, 1.0, v96
	v_cndmask_b32_e32 v130, v223, v131, vcc
	v_add_f32_e32 v130, 1.0, v130
	v_div_scale_f32 v131, s[0:1], v130, v130, 1.0
	v_rcp_f32_e32 v132, v131
	v_exp_f32_e32 v92, v92
	v_mul_f32_e32 v97, 0xbfb8aa3b, v97
	v_exp_f32_e32 v97, v97
	v_fma_f32 v134, -v131, v132, 1.0
	v_fmac_f32_e32 v132, v134, v132
	v_div_scale_f32 v134, vcc, 1.0, v130, 1.0
	v_mul_f32_e32 v135, v134, v132
	v_fma_f32 v136, -v131, v135, v134
	v_fmac_f32_e32 v135, v136, v132
	v_fma_f32 v131, -v131, v135, v134
	v_div_fmas_f32 v131, v131, v132, v135
	v_div_fixup_f32 v181, v131, v130, 1.0
	v_sub_f32_e32 v130, v137, v133
	v_mul_f32_e32 v131, 0x3fb8aa3b, v130
	v_fma_f32 v132, v130, s9, -v131
	v_rndne_f32_e32 v133, v131
	v_fmac_f32_e32 v132, 0x32a5705f, v130
	v_sub_f32_e32 v131, v131, v133
	v_add_f32_e32 v131, v131, v132
	v_exp_f32_e32 v131, v131
	v_cvt_i32_f32_e32 v132, v133
	v_cmp_ngt_f32_e32 vcc, s95, v130
	v_pk_add_f32 v[202:203], v[180:181], 1.0 op_sel_hi:[1,0] neg_lo:[1,0] neg_hi:[1,0]
	v_add_f32_e32 v92, 1.0, v92
	v_ldexp_f32 v131, v131, v132
	v_cndmask_b32_e32 v131, 0, v131, vcc
	v_cmp_nlt_f32_e32 vcc, s85, v130
	v_mul_f32_e32 v93, 0xbfb8aa3b, v93
	v_add_f32_e32 v97, 1.0, v97
	v_cndmask_b32_e32 v130, v223, v131, vcc
	v_add_f32_e32 v130, 1.0, v130
	v_div_scale_f32 v131, s[0:1], v130, v130, 1.0
	v_rcp_f32_e32 v132, v131
	v_exp_f32_e32 v93, v93
	v_mul_f32_e32 v86, 0xbfb8aa3b, v86
	v_exp_f32_e32 v86, v86
	v_fma_f32 v133, -v131, v132, 1.0
	v_fmac_f32_e32 v132, v133, v132
	v_div_scale_f32 v133, vcc, 1.0, v130, 1.0
	v_mul_f32_e32 v134, v133, v132
	v_fma_f32 v135, -v131, v134, v133
	v_fmac_f32_e32 v134, v135, v132
	v_fma_f32 v131, -v131, v134, v133
	v_div_fmas_f32 v131, v131, v132, v134
	v_div_fixup_f32 v179, v131, v130, 1.0
	global_load_dwordx4 v[130:133], v[186:187], off offset:-3568
	global_load_dwordx4 v[138:141], v[186:187], off offset:-3584
	global_load_dwordx4 v[134:137], v[186:187], off offset:528
	global_load_dwordx4 v[142:145], v[186:187], off offset:512
	v_pk_add_f32 v[200:201], v[178:179], 1.0 op_sel_hi:[1,0] neg_lo:[1,0] neg_hi:[1,0]
	v_rcp_f32_e32 v186, v119
	v_add_f32_e32 v93, 1.0, v93
	v_mul_f32_e32 v82, 0xbfb8aa3b, v82
	v_add_f32_e32 v86, 1.0, v86
	v_exp_f32_e32 v82, v82
	v_mul_f32_e32 v87, 0xbfb8aa3b, v87
	v_exp_f32_e32 v87, v87
	v_mul_f32_e32 v83, 0xbfb8aa3b, v83
	v_add_f32_e32 v82, 1.0, v82
	v_exp_f32_e32 v83, v83
	v_add_f32_e32 v87, 1.0, v87
	v_mul_f32_e32 v88, 0xbfb8aa3b, v88
	v_exp_f32_e32 v88, v88
	v_add_f32_e32 v83, 1.0, v83
	v_mul_f32_e32 v84, 0xbfb8aa3b, v84
	v_exp_f32_e32 v84, v84
	v_add_f32_e32 v88, 1.0, v88
	v_mul_f32_e32 v89, 0xbfb8aa3b, v89
	v_exp_f32_e32 v89, v89
	v_add_f32_e32 v84, 1.0, v84
	v_mul_f32_e32 v85, 0xbfb8aa3b, v85
	v_exp_f32_e32 v85, v85
	v_add_f32_e32 v89, 1.0, v89
	v_mul_f32_e32 v78, 0xbfb8aa3b, v78
	v_exp_f32_e32 v78, v78
	v_add_f32_e32 v85, 1.0, v85
	v_mul_f32_e32 v74, 0xbfb8aa3b, v74
	v_exp_f32_e32 v74, v74
	v_add_f32_e32 v78, 1.0, v78
	v_mul_f32_e32 v79, 0xbfb8aa3b, v79
	v_exp_f32_e32 v79, v79
	v_add_f32_e32 v74, 1.0, v74
	v_mul_f32_e32 v75, 0xbfb8aa3b, v75
	v_exp_f32_e32 v75, v75
	v_add_f32_e32 v79, 1.0, v79
	v_mul_f32_e32 v80, 0xbfb8aa3b, v80
	v_exp_f32_e32 v80, v80
	v_add_f32_e32 v75, 1.0, v75
	v_mul_f32_e32 v76, 0xbfb8aa3b, v76
	v_exp_f32_e32 v76, v76
	v_add_f32_e32 v80, 1.0, v80
	v_mul_f32_e32 v81, 0xbfb8aa3b, v81
	v_exp_f32_e32 v81, v81
	v_add_f32_e32 v76, 1.0, v76
	v_mul_f32_e32 v77, 0xbfb8aa3b, v77
	v_exp_f32_e32 v77, v77
	v_add_f32_e32 v81, 1.0, v81
	v_mul_f32_e32 v70, 0xbfb8aa3b, v70
	v_exp_f32_e32 v70, v70
	v_add_f32_e32 v77, 1.0, v77
	v_mul_f32_e32 v66, 0xbfb8aa3b, v66
	v_exp_f32_e32 v66, v66
	v_add_f32_e32 v70, 1.0, v70
	v_mul_f32_e32 v71, 0xbfb8aa3b, v71
	v_exp_f32_e32 v71, v71
	v_add_f32_e32 v66, 1.0, v66
	v_mul_f32_e32 v67, 0xbfb8aa3b, v67
	v_exp_f32_e32 v67, v67
	v_add_f32_e32 v71, 1.0, v71
	v_mul_f32_e32 v72, 0xbfb8aa3b, v72
	v_exp_f32_e32 v72, v72
	v_add_f32_e32 v67, 1.0, v67
	v_mul_f32_e32 v68, 0xbfb8aa3b, v68
	v_exp_f32_e32 v68, v68
	v_add_f32_e32 v72, 1.0, v72
	v_mul_f32_e32 v73, 0xbfb8aa3b, v73
	v_exp_f32_e32 v73, v73
	v_add_f32_e32 v68, 1.0, v68
	v_mul_f32_e32 v69, 0xbfb8aa3b, v69
	v_exp_f32_e32 v69, v69
	v_add_f32_e32 v73, 1.0, v73
	v_mul_f32_e32 v62, 0xbfb8aa3b, v62
	v_exp_f32_e32 v62, v62
	v_add_f32_e32 v69, 1.0, v69
	v_mul_f32_e32 v58, 0xbfb8aa3b, v58
	v_exp_f32_e32 v58, v58
	v_add_f32_e32 v62, 1.0, v62
	s_waitcnt vmcnt(1)
	v_sub_f32_e32 v130, v134, v130
	s_waitcnt vmcnt(0)
	v_sub_f32_e32 v138, v142, v138
	v_mul_f32_e32 v142, 0x3fb8aa3b, v138
	v_fma_f32 v154, v138, s9, -v142
	v_rndne_f32_e32 v170, v142
	v_fmac_f32_e32 v154, 0x32a5705f, v138
	v_sub_f32_e32 v142, v142, v170
	v_add_f32_e32 v142, v142, v154
	v_exp_f32_e32 v142, v142
	v_cvt_i32_f32_e32 v154, v170
	v_cmp_ngt_f32_e32 vcc, s95, v138
	v_mul_f32_e32 v134, 0x3fb8aa3b, v130
	v_add_f32_e32 v58, 1.0, v58
	v_ldexp_f32 v142, v142, v154
	v_cndmask_b32_e32 v142, 0, v142, vcc
	v_cmp_nlt_f32_e32 vcc, s85, v138
	v_mul_f32_e32 v63, 0xbfb8aa3b, v63
	v_exp_f32_e32 v63, v63
	v_cndmask_b32_e32 v138, v223, v142, vcc
	v_add_f32_e32 v138, 1.0, v138
	v_div_scale_f32 v142, s[0:1], v138, v138, 1.0
	v_rcp_f32_e32 v154, v142
	v_mul_f32_e32 v59, 0xbfb8aa3b, v59
	v_add_f32_e32 v63, 1.0, v63
	v_exp_f32_e32 v59, v59
	v_fma_f32 v170, -v142, v154, 1.0
	v_fmac_f32_e32 v154, v170, v154
	v_div_scale_f32 v170, vcc, 1.0, v138, 1.0
	v_mul_f32_e32 v172, v170, v154
	v_fma_f32 v174, -v142, v172, v170
	v_fmac_f32_e32 v172, v174, v154
	v_fma_f32 v142, -v142, v172, v170
	v_div_fmas_f32 v142, v142, v154, v172
	v_div_fixup_f32 v189, v142, v138, 1.0
	v_sub_f32_e32 v138, v143, v139
	v_mul_f32_e32 v139, 0x3fb8aa3b, v138
	v_fma_f32 v142, v138, s9, -v139
	v_rndne_f32_e32 v143, v139
	v_fmac_f32_e32 v142, 0x32a5705f, v138
	v_sub_f32_e32 v139, v139, v143
	v_add_f32_e32 v139, v139, v142
	v_exp_f32_e32 v139, v139
	v_cvt_i32_f32_e32 v142, v143
	v_cmp_ngt_f32_e32 vcc, s95, v138
	v_rcp_f32_e32 v172, v127
	v_rcp_f32_e32 v174, v128
	v_ldexp_f32 v139, v139, v142
	v_cndmask_b32_e32 v139, 0, v139, vcc
	v_cmp_nlt_f32_e32 vcc, s85, v138
	v_pk_add_f32 v[190:191], v[172:173], 1.0 op_sel_hi:[1,0] neg_lo:[1,0] neg_hi:[1,0]
	v_add_f32_e32 v59, 1.0, v59
	v_cndmask_b32_e32 v138, v223, v139, vcc
	v_add_f32_e32 v138, 1.0, v138
	v_div_scale_f32 v139, s[0:1], v138, v138, 1.0
	v_rcp_f32_e32 v142, v139
	v_fma_f32 v123, v172, v191, v173
	v_mul_f32_e32 v64, 0xbfb8aa3b, v64
	v_exp_f32_e32 v64, v64
	v_fma_f32 v143, -v139, v142, 1.0
	v_fmac_f32_e32 v142, v143, v142
	v_div_scale_f32 v143, vcc, 1.0, v138, 1.0
	v_mul_f32_e32 v154, v143, v142
	v_fma_f32 v170, -v139, v154, v143
	v_fmac_f32_e32 v154, v170, v142
	v_fma_f32 v139, -v139, v154, v143
	v_div_fmas_f32 v139, v139, v142, v154
	v_div_fixup_f32 v187, v139, v138, 1.0
	v_sub_f32_e32 v138, v144, v140
	v_mul_f32_e32 v139, 0x3fb8aa3b, v138
	v_fma_f32 v140, v138, s9, -v139
	v_rndne_f32_e32 v142, v139
	v_fmac_f32_e32 v140, 0x32a5705f, v138
	v_sub_f32_e32 v139, v139, v142
	v_add_f32_e32 v139, v139, v140
	v_exp_f32_e32 v139, v139
	v_cvt_i32_f32_e32 v140, v142
	v_cmp_ngt_f32_e32 vcc, s95, v138
	v_rcp_f32_e32 v170, v126
	v_mul_f32_e32 v60, 0xbfb8aa3b, v60
	v_ldexp_f32 v139, v139, v140
	v_cndmask_b32_e32 v139, 0, v139, vcc
	v_cmp_nlt_f32_e32 vcc, s85, v138
	v_pk_add_f32 v[192:193], v[170:171], 1.0 op_sel_hi:[1,0] neg_lo:[1,0] neg_hi:[1,0]
	v_add_f32_e32 v64, 1.0, v64
	v_cndmask_b32_e32 v138, v223, v139, vcc
	v_add_f32_e32 v138, 1.0, v138
	v_div_scale_f32 v139, s[0:1], v138, v138, 1.0
	v_rcp_f32_e32 v140, v139
	v_fma_f32 v122, v170, v193, v171
	v_exp_f32_e32 v60, v60
	v_mul_f32_e32 v65, 0xbfb8aa3b, v65
	v_fma_f32 v142, -v139, v140, 1.0
	v_fmac_f32_e32 v140, v142, v140
	v_div_scale_f32 v142, vcc, 1.0, v138, 1.0
	v_mul_f32_e32 v143, v142, v140
	v_fma_f32 v144, -v139, v143, v142
	v_fmac_f32_e32 v143, v144, v140
	v_fma_f32 v139, -v139, v143, v142
	v_div_fmas_f32 v139, v139, v140, v143
	v_div_fixup_f32 v143, v139, v138, 1.0
	v_sub_f32_e32 v138, v145, v141
	v_mul_f32_e32 v139, 0x3fb8aa3b, v138
	v_fma_f32 v140, v138, s9, -v139
	v_rndne_f32_e32 v141, v139
	v_fmac_f32_e32 v140, 0x32a5705f, v138
	v_sub_f32_e32 v139, v139, v141
	v_add_f32_e32 v139, v139, v140
	v_exp_f32_e32 v139, v139
	v_cvt_i32_f32_e32 v140, v141
	v_cmp_ngt_f32_e32 vcc, s95, v138
	v_add_f32_e32 v60, 1.0, v60
	v_exp_f32_e32 v65, v65
	v_ldexp_f32 v139, v139, v140
	v_cndmask_b32_e32 v139, 0, v139, vcc
	v_cmp_nlt_f32_e32 vcc, s85, v138
	v_mul_f32_e32 v61, 0xbfb8aa3b, v61
	v_add_f32_e32 v65, 1.0, v65
	v_cndmask_b32_e32 v138, v223, v139, vcc
	v_add_f32_e32 v138, 1.0, v138
	v_div_scale_f32 v139, s[0:1], v138, v138, 1.0
	v_rcp_f32_e32 v140, v139
	v_exp_f32_e32 v61, v61
	v_mul_f32_e32 v54, 0xbfb8aa3b, v54
	v_exp_f32_e32 v54, v54
	v_fma_f32 v141, -v139, v140, 1.0
	v_fmac_f32_e32 v140, v141, v140
	v_div_scale_f32 v141, vcc, 1.0, v138, 1.0
	v_mul_f32_e32 v142, v141, v140
	v_fma_f32 v144, -v139, v142, v141
	v_fmac_f32_e32 v142, v144, v140
	v_fma_f32 v139, -v139, v142, v141
	v_div_fmas_f32 v139, v139, v140, v142
	v_div_fixup_f32 v139, v139, v138, 1.0
	v_fma_f32 v138, v130, s9, -v134
	v_rndne_f32_e32 v140, v134
	v_fmac_f32_e32 v138, 0x32a5705f, v130
	v_sub_f32_e32 v134, v134, v140
	v_add_f32_e32 v134, v134, v138
	v_exp_f32_e32 v134, v134
	v_cvt_i32_f32_e32 v138, v140
	v_cmp_ngt_f32_e32 vcc, s95, v130
	v_add_f32_e32 v61, 1.0, v61
	v_mul_f32_e32 v50, 0xbfb8aa3b, v50
	v_ldexp_f32 v134, v134, v138
	v_cndmask_b32_e32 v134, 0, v134, vcc
	v_cmp_nlt_f32_e32 vcc, s85, v130
	v_add_f32_e32 v54, 1.0, v54
	v_exp_f32_e32 v50, v50
	v_cndmask_b32_e32 v130, v223, v134, vcc
	v_add_f32_e32 v130, 1.0, v130
	v_div_scale_f32 v134, s[0:1], v130, v130, 1.0
	v_rcp_f32_e32 v138, v134
	v_add_f32_e32 v50, 1.0, v50
	v_mul_f32_e32 v55, 0xbfb8aa3b, v55
	v_exp_f32_e32 v55, v55
	v_fma_f32 v140, -v134, v138, 1.0
	v_fmac_f32_e32 v138, v140, v138
	v_div_scale_f32 v140, vcc, 1.0, v130, 1.0
	v_mul_f32_e32 v141, v140, v138
	v_fma_f32 v142, -v134, v141, v140
	v_fmac_f32_e32 v141, v142, v138
	v_fma_f32 v134, -v134, v141, v140
	v_div_fmas_f32 v134, v134, v138, v141
	v_div_fixup_f32 v145, v134, v130, 1.0
	v_sub_f32_e32 v130, v135, v131
	v_mul_f32_e32 v131, 0x3fb8aa3b, v130
	v_fma_f32 v134, v130, s9, -v131
	v_rndne_f32_e32 v135, v131
	v_fmac_f32_e32 v134, 0x32a5705f, v130
	v_sub_f32_e32 v131, v131, v135
	v_add_f32_e32 v131, v131, v134
	v_exp_f32_e32 v131, v131
	v_cvt_i32_f32_e32 v134, v135
	v_cmp_ngt_f32_e32 vcc, s95, v130
	v_mul_f32_e32 v142, v202, v203
	v_mul_f32_e32 v51, 0xbfb8aa3b, v51
	v_ldexp_f32 v131, v131, v134
	v_cndmask_b32_e32 v131, 0, v131, vcc
	v_cmp_nlt_f32_e32 vcc, s85, v130
	v_add_f32_e32 v55, 1.0, v55
	v_exp_f32_e32 v51, v51
	v_cndmask_b32_e32 v130, v223, v131, vcc
	v_add_f32_e32 v130, 1.0, v130
	v_div_scale_f32 v131, s[0:1], v130, v130, 1.0
	v_rcp_f32_e32 v134, v131
	v_add_f32_e32 v51, 1.0, v51
	v_mul_f32_e32 v56, 0xbfb8aa3b, v56
	v_exp_f32_e32 v56, v56
	v_fma_f32 v135, -v131, v134, 1.0
	v_fmac_f32_e32 v134, v135, v134
	v_div_scale_f32 v135, vcc, 1.0, v130, 1.0
	v_mul_f32_e32 v138, v135, v134
	v_fma_f32 v140, -v131, v138, v135
	v_fmac_f32_e32 v138, v140, v134
	v_fma_f32 v131, -v131, v138, v135
	v_div_fmas_f32 v131, v131, v134, v138
	v_div_fixup_f32 v141, v131, v130, 1.0
	v_sub_f32_e32 v130, v136, v132
	v_mul_f32_e32 v131, 0x3fb8aa3b, v130
	v_fma_f32 v132, v130, s9, -v131
	v_rndne_f32_e32 v134, v131
	v_fmac_f32_e32 v132, 0x32a5705f, v130
	v_sub_f32_e32 v131, v131, v134
	v_add_f32_e32 v131, v131, v132
	v_exp_f32_e32 v131, v131
	v_cvt_i32_f32_e32 v132, v134
	v_cmp_ngt_f32_e32 vcc, s95, v130
	v_mul_f32_e32 v138, v190, v191
	v_mul_f32_e32 v140, v204, v205
	v_ldexp_f32 v131, v131, v132
	v_cndmask_b32_e32 v131, 0, v131, vcc
	v_cmp_nlt_f32_e32 vcc, s85, v130
	v_mul_f32_e32 v52, 0xbfb8aa3b, v52
	v_add_f32_e32 v56, 1.0, v56
	v_cndmask_b32_e32 v130, v223, v131, vcc
	v_add_f32_e32 v130, 1.0, v130
	v_div_scale_f32 v131, s[0:1], v130, v130, 1.0
	v_rcp_f32_e32 v132, v131
	v_exp_f32_e32 v52, v52
	v_mul_f32_e32 v57, 0xbfb8aa3b, v57
	v_exp_f32_e32 v57, v57
	v_fma_f32 v134, -v131, v132, 1.0
	v_fmac_f32_e32 v132, v134, v132
	v_div_scale_f32 v134, vcc, 1.0, v130, 1.0
	v_mul_f32_e32 v135, v134, v132
	v_fma_f32 v136, -v131, v135, v134
	v_fmac_f32_e32 v135, v136, v132
	v_fma_f32 v131, -v131, v135, v134
	v_div_fmas_f32 v131, v131, v132, v135
	v_div_fixup_f32 v135, v131, v130, 1.0
	v_sub_f32_e32 v130, v137, v133
	v_mul_f32_e32 v131, 0x3fb8aa3b, v130
	v_fma_f32 v132, v130, s9, -v131
	v_rndne_f32_e32 v133, v131
	v_fmac_f32_e32 v132, 0x32a5705f, v130
	v_sub_f32_e32 v131, v131, v133
	v_add_f32_e32 v131, v131, v132
	v_exp_f32_e32 v131, v131
	v_cvt_i32_f32_e32 v132, v133
	v_cmp_ngt_f32_e32 vcc, s95, v130
	v_add_f32_e32 v52, 1.0, v52
	v_mul_f32_e32 v53, 0xbfb8aa3b, v53
	v_ldexp_f32 v131, v131, v132
	v_cndmask_b32_e32 v131, 0, v131, vcc
	v_cmp_nlt_f32_e32 vcc, s85, v130
	v_add_f32_e32 v57, 1.0, v57
	v_exp_f32_e32 v53, v53
	v_cndmask_b32_e32 v130, v223, v131, vcc
	v_add_f32_e32 v130, 1.0, v130
	v_div_scale_f32 v131, s[0:1], v130, v130, 1.0
	v_rcp_f32_e32 v132, v131
	v_add_f32_e32 v53, 1.0, v53
	v_mul_f32_e32 v46, 0xbfb8aa3b, v46
	v_exp_f32_e32 v46, v46
	v_fma_f32 v133, -v131, v132, 1.0
	v_fmac_f32_e32 v132, v133, v132
	v_div_scale_f32 v133, vcc, 1.0, v130, 1.0
	v_mul_f32_e32 v134, v133, v132
	v_fma_f32 v136, -v131, v134, v133
	v_fmac_f32_e32 v134, v136, v132
	v_fma_f32 v131, -v131, v134, v133
	v_div_fmas_f32 v131, v131, v132, v134
	v_cmp_gt_f32_e32 vcc, s16, v122
	v_pk_add_f32 v[136:137], v[174:175], 1.0 op_sel_hi:[1,0] neg_lo:[1,0] neg_hi:[1,0]
	v_div_fixup_f32 v131, v131, v130, 1.0
	v_cndmask_b32_e64 v126, 0, 32, vcc
	v_ldexp_f32 v122, v122, v126
	v_log_f32_e32 v122, v122
	v_fma_f32 v124, v174, v137, v175
	v_mul_f32_e32 v130, v192, v193
	v_mul_f32_e32 v134, v206, v207
	v_mul_f32_e32 v126, 0x3f317217, v122
	v_fma_f32 v126, v122, s17, -v126
	v_fmac_f32_e32 v126, 0x3377d1cf, v122
	v_fmac_f32_e32 v126, 0x3f317217, v122
	v_cmp_lt_f32_e64 s[0:1], |v122|, s86
	v_mul_f32_e32 v136, v136, v137
	v_mul_f32_e32 v42, 0xbfb8aa3b, v42
	v_cndmask_b32_e64 v122, v122, v126, s[0:1]
	v_cndmask_b32_e32 v126, 0, v224, vcc
	v_sub_f32_e32 v122, v122, v126
	v_fma_f32 v126, v184, v207, v185
	v_cmp_gt_f32_e32 vcc, s16, v126
	v_add_f32_e32 v46, 1.0, v46
	v_exp_f32_e32 v42, v42
	v_cndmask_b32_e64 v132, 0, 32, vcc
	v_ldexp_f32 v126, v126, v132
	v_log_f32_e32 v126, v126
	v_add_f32_e32 v42, 1.0, v42
	v_mul_f32_e32 v47, 0xbfb8aa3b, v47
	v_exp_f32_e32 v47, v47
	v_mul_f32_e32 v132, 0x3f317217, v126
	v_fma_f32 v132, v126, s17, -v132
	v_fmac_f32_e32 v132, 0x3377d1cf, v126
	v_fmac_f32_e32 v132, 0x3f317217, v126
	v_cmp_lt_f32_e64 s[0:1], |v126|, s86
	v_mul_f32_e32 v43, 0xbfb8aa3b, v43
	v_add_f32_e32 v47, 1.0, v47
	v_cndmask_b32_e64 v126, v126, v132, s[0:1]
	v_cndmask_b32_e32 v132, 0, v224, vcc
	v_cmp_gt_f32_e32 vcc, s16, v123
	v_sub_f32_e32 v126, v126, v132
	v_exp_f32_e32 v43, v43
	v_cndmask_b32_e64 v127, 0, 32, vcc
	v_ldexp_f32 v123, v123, v127
	v_log_f32_e32 v123, v123
	v_add_f32_e32 v43, 1.0, v43
	v_mul_f32_e32 v48, 0xbfb8aa3b, v48
	v_exp_f32_e32 v48, v48
	v_mul_f32_e32 v127, 0x3f317217, v123
	v_fma_f32 v127, v123, s17, -v127
	v_fmac_f32_e32 v127, 0x3377d1cf, v123
	v_fmac_f32_e32 v127, 0x3f317217, v123
	v_cmp_lt_f32_e64 s[0:1], |v123|, s86
	v_mul_f32_e32 v44, 0xbfb8aa3b, v44
	v_add_f32_e32 v48, 1.0, v48
	v_cndmask_b32_e64 v123, v123, v127, s[0:1]
	v_cndmask_b32_e32 v127, 0, v224, vcc
	v_sub_f32_e32 v123, v123, v127
	v_fma_f32 v127, v182, v205, v183
	v_cmp_gt_f32_e32 vcc, s16, v127
	v_exp_f32_e32 v44, v44
	v_mul_f32_e32 v49, 0xbfb8aa3b, v49
	v_cndmask_b32_e64 v132, 0, 32, vcc
	v_ldexp_f32 v127, v127, v132
	v_log_f32_e32 v127, v127
	v_add_f32_e32 v44, 1.0, v44
	v_exp_f32_e32 v49, v49
	v_mul_f32_e32 v45, 0xbfb8aa3b, v45
	v_mul_f32_e32 v132, 0x3f317217, v127
	v_fma_f32 v132, v127, s17, -v132
	v_fmac_f32_e32 v132, 0x3377d1cf, v127
	v_fmac_f32_e32 v132, 0x3f317217, v127
	v_cmp_lt_f32_e64 s[0:1], |v127|, s86
	v_add_f32_e32 v49, 1.0, v49
	v_exp_f32_e32 v45, v45
	v_cndmask_b32_e64 v127, v127, v132, s[0:1]
	v_cndmask_b32_e32 v132, 0, v224, vcc
	v_cmp_gt_f32_e32 vcc, s16, v124
	v_sub_f32_e32 v127, v127, v132
	v_add_f32_e32 v45, 1.0, v45
	v_cndmask_b32_e64 v128, 0, 32, vcc
	v_ldexp_f32 v124, v124, v128
	v_log_f32_e32 v124, v124
	v_mul_f32_e32 v38, 0xbfb8aa3b, v38
	v_exp_f32_e32 v38, v38
	v_mul_f32_e32 v34, 0xbfb8aa3b, v34
	v_mul_f32_e32 v128, 0x3f317217, v124
	v_fma_f32 v128, v124, s17, -v128
	v_fmac_f32_e32 v128, 0x3377d1cf, v124
	v_fmac_f32_e32 v128, 0x3f317217, v124
	v_cmp_lt_f32_e64 s[0:1], |v124|, s86
	v_add_f32_e32 v38, 1.0, v38
	v_exp_f32_e32 v34, v34
	v_cndmask_b32_e64 v124, v124, v128, s[0:1]
	v_cndmask_b32_e32 v128, 0, v224, vcc
	v_sub_f32_e32 v124, v124, v128
	v_fma_f32 v128, v180, v203, v181
	v_cmp_gt_f32_e32 vcc, s16, v128
	v_add_f32_e32 v34, 1.0, v34
	v_mul_f32_e32 v39, 0xbfb8aa3b, v39
	v_cndmask_b32_e64 v132, 0, 32, vcc
	v_ldexp_f32 v128, v128, v132
	v_log_f32_e32 v128, v128
	v_exp_f32_e32 v39, v39
	v_mul_f32_e32 v35, 0xbfb8aa3b, v35
	v_exp_f32_e32 v35, v35
	v_mul_f32_e32 v132, 0x3f317217, v128
	v_fma_f32 v132, v128, s17, -v132
	v_fmac_f32_e32 v132, 0x3377d1cf, v128
	v_fmac_f32_e32 v132, 0x3f317217, v128
	v_cmp_lt_f32_e64 s[0:1], |v128|, s86
	v_add_f32_e32 v39, 1.0, v39
	v_add_f32_e32 v35, 1.0, v35
	v_cndmask_b32_e64 v128, v128, v132, s[0:1]
	v_cndmask_b32_e32 v132, 0, v224, vcc
	v_sub_f32_e32 v128, v128, v132
	v_pk_add_f32 v[132:133], v[176:177], 1.0 op_sel_hi:[1,0] neg_lo:[1,0] neg_hi:[1,0]
	v_mul_f32_e32 v40, 0xbfb8aa3b, v40
	v_fma_f32 v125, v176, v133, v177
	v_cmp_gt_f32_e32 vcc, s16, v125
	v_mul_f32_e32 v132, v132, v133
	v_exp_f32_e32 v40, v40
	v_cndmask_b32_e64 v129, 0, 32, vcc
	v_ldexp_f32 v125, v125, v129
	v_log_f32_e32 v125, v125
	v_mul_f32_e32 v36, 0xbfb8aa3b, v36
	v_add_f32_e32 v40, 1.0, v40
	v_exp_f32_e32 v36, v36
	v_mul_f32_e32 v129, 0x3f317217, v125
	v_fma_f32 v129, v125, s17, -v129
	v_fmac_f32_e32 v129, 0x3377d1cf, v125
	v_fmac_f32_e32 v129, 0x3f317217, v125
	v_cmp_lt_f32_e64 s[0:1], |v125|, s86
	v_add_f32_e32 v36, 1.0, v36
	v_mul_f32_e32 v41, 0xbfb8aa3b, v41
	v_cndmask_b32_e64 v125, v125, v129, s[0:1]
	v_cndmask_b32_e32 v129, 0, v224, vcc
	v_sub_f32_e32 v125, v125, v129
	v_fma_f32 v129, v178, v201, v179
	v_cmp_gt_f32_e32 vcc, s16, v129
	v_exp_f32_e32 v41, v41
	v_mul_f32_e32 v37, 0xbfb8aa3b, v37
	v_cndmask_b32_e64 v144, 0, 32, vcc
	v_ldexp_f32 v129, v129, v144
	v_log_f32_e32 v129, v129
	v_add_f32_e32 v41, 1.0, v41
	v_exp_f32_e32 v37, v37
	v_mul_f32_e32 v30, 0xbfb8aa3b, v30
	v_mul_f32_e32 v144, 0x3f317217, v129
	v_fma_f32 v144, v129, s17, -v144
	v_fmac_f32_e32 v144, 0x3377d1cf, v129
	v_fmac_f32_e32 v144, 0x3f317217, v129
	v_cmp_lt_f32_e64 s[0:1], |v129|, s86
	v_add_f32_e32 v37, 1.0, v37
	v_exp_f32_e32 v30, v30
	v_cndmask_b32_e64 v129, v129, v144, s[0:1]
	v_cndmask_b32_e32 v144, 0, v224, vcc
	v_sub_f32_e32 v129, v129, v144
	v_mul_f32_e32 v144, v200, v201
	global_store_dwordx4 v[212:213], v[122:125], off offset:-4096 nt
	global_store_dwordx4 v[212:213], v[126:129], off offset:-4080 nt
	v_mul_f32_e32 v26, 0xbfb8aa3b, v26
	v_cvt_pk_bf16_f32 v122, v130, v138
	v_cvt_pk_bf16_f32 v123, v136, v132
	v_cvt_pk_bf16_f32 v124, v134, v140
	v_cvt_pk_bf16_f32 v125, v142, v144
	s_nop 0
	v_pk_add_f32 v[128:129], v[188:189], 1.0 op_sel_hi:[1,0] neg_lo:[1,0] neg_hi:[1,0]
	v_rcp_f32_e32 v144, v114
	v_fma_f32 v114, v188, v129, v189
	v_cmp_gt_f32_e32 vcc, s16, v114
	v_mad_i64_i32 v[126:127], s[0:1], v164, s8, v[208:209]
	s_nop 0
	v_cndmask_b32_e64 v118, 0, 32, vcc
	v_ldexp_f32 v114, v114, v118
	v_log_f32_e32 v114, v114
	v_pk_add_f32 v[198:199], v[144:145], 1.0 op_sel_hi:[1,0] neg_lo:[1,0] neg_hi:[1,0]
	v_lshl_add_u64 v[214:215], v[126:127], 0, v[210:211]
	global_store_dwordx4 v[214:215], v[122:125], off nt
	v_mul_f32_e32 v118, 0x3f317217, v114
	v_fma_f32 v118, v114, s17, -v118
	v_fmac_f32_e32 v118, 0x3377d1cf, v114
	v_fmac_f32_e32 v118, 0x3f317217, v114
	v_cmp_lt_f32_e64 s[0:1], |v114|, s86
	v_pk_add_f32 v[126:127], v[186:187], 1.0 op_sel_hi:[1,0] neg_lo:[1,0] neg_hi:[1,0]
	v_rcp_f32_e32 v140, v115
	v_cndmask_b32_e64 v114, v114, v118, s[0:1]
	v_cndmask_b32_e32 v118, 0, v224, vcc
	v_sub_f32_e32 v114, v114, v118
	v_fma_f32 v118, v144, v199, v145
	v_cmp_gt_f32_e32 vcc, s16, v118
	v_fma_f32 v115, v186, v127, v187
	v_pk_add_f32 v[196:197], v[140:141], 1.0 op_sel_hi:[1,0] neg_lo:[1,0] neg_hi:[1,0]
	v_cndmask_b32_e64 v122, 0, 32, vcc
	v_ldexp_f32 v118, v118, v122
	v_log_f32_e32 v118, v118
	v_rcp_f32_e32 v142, v120
	v_rcp_f32_e32 v134, v116
	v_rcp_f32_e32 v138, v121
	v_mul_f32_e32 v122, 0x3f317217, v118
	v_fma_f32 v122, v118, s17, -v122
	v_fmac_f32_e32 v122, 0x3377d1cf, v118
	v_fmac_f32_e32 v122, 0x3f317217, v118
	v_cmp_lt_f32_e64 s[0:1], |v118|, s86
	v_pk_add_f32 v[124:125], v[142:143], 1.0 op_sel_hi:[1,0] neg_lo:[1,0] neg_hi:[1,0]
	v_pk_add_f32 v[194:195], v[134:135], 1.0 op_sel_hi:[1,0] neg_lo:[1,0] neg_hi:[1,0]
	v_cndmask_b32_e64 v118, v118, v122, s[0:1]
	v_cndmask_b32_e32 v122, 0, v224, vcc
	v_cmp_gt_f32_e32 vcc, s16, v115
	v_sub_f32_e32 v118, v118, v122
	v_fma_f32 v116, v142, v125, v143
	v_cndmask_b32_e64 v119, 0, 32, vcc
	v_ldexp_f32 v115, v115, v119
	v_log_f32_e32 v115, v115
	v_rcp_f32_e32 v130, v117
	v_mul_f32_e32 v128, v128, v129
	v_mul_f32_e32 v126, v126, v127
	v_mul_f32_e32 v119, 0x3f317217, v115
	v_fma_f32 v119, v115, s17, -v119
	v_fmac_f32_e32 v119, 0x3377d1cf, v115
	v_fmac_f32_e32 v119, 0x3f317217, v115
	v_cmp_lt_f32_e64 s[0:1], |v115|, s86
	v_pk_add_f32 v[166:167], v[130:131], 1.0 op_sel_hi:[1,0] neg_lo:[1,0] neg_hi:[1,0]
	v_mul_f32_e32 v132, v198, v199
	v_cndmask_b32_e64 v115, v115, v119, s[0:1]
	v_cndmask_b32_e32 v119, 0, v224, vcc
	v_sub_f32_e32 v115, v115, v119
	v_fma_f32 v119, v140, v197, v141
	v_cmp_gt_f32_e32 vcc, s16, v119
	v_mul_f32_e32 v136, v196, v197
	v_mul_f32_e32 v124, v124, v125
	v_cndmask_b32_e64 v122, 0, 32, vcc
	v_ldexp_f32 v119, v119, v122
	v_log_f32_e32 v119, v119
	v_add_f32_e32 v30, 1.0, v30
	v_exp_f32_e32 v26, v26
	v_mul_f32_e32 v31, 0xbfb8aa3b, v31
	v_mul_f32_e32 v122, 0x3f317217, v119
	v_fma_f32 v122, v119, s17, -v122
	v_fmac_f32_e32 v122, 0x3377d1cf, v119
	v_fmac_f32_e32 v122, 0x3f317217, v119
	v_cmp_lt_f32_e64 s[0:1], |v119|, s86
	v_add_f32_e32 v26, 1.0, v26
	v_exp_f32_e32 v31, v31
	v_cndmask_b32_e64 v119, v119, v122, s[0:1]
	v_cndmask_b32_e32 v122, 0, v224, vcc
	v_cmp_gt_f32_e32 vcc, s16, v116
	v_sub_f32_e32 v119, v119, v122
	v_mul_f32_e32 v27, 0xbfb8aa3b, v27
	v_cndmask_b32_e64 v120, 0, 32, vcc
	v_ldexp_f32 v116, v116, v120
	v_log_f32_e32 v116, v116
	v_add_f32_e32 v31, 1.0, v31
	v_exp_f32_e32 v27, v27
	v_mul_f32_e32 v32, 0xbfb8aa3b, v32
	v_mul_f32_e32 v120, 0x3f317217, v116
	v_fma_f32 v120, v116, s17, -v120
	v_fmac_f32_e32 v120, 0x3377d1cf, v116
	v_fmac_f32_e32 v120, 0x3f317217, v116
	v_cmp_lt_f32_e64 s[0:1], |v116|, s86
	v_add_f32_e32 v27, 1.0, v27
	v_exp_f32_e32 v32, v32
	v_cndmask_b32_e64 v116, v116, v120, s[0:1]
	v_cndmask_b32_e32 v120, 0, v224, vcc
	v_sub_f32_e32 v116, v116, v120
	v_fma_f32 v120, v134, v195, v135
	v_cmp_gt_f32_e32 vcc, s16, v120
	v_mul_f32_e32 v134, v194, v195
	v_mul_f32_e32 v28, 0xbfb8aa3b, v28
	v_cndmask_b32_e64 v122, 0, 32, vcc
	v_ldexp_f32 v120, v120, v122
	v_log_f32_e32 v120, v120
	v_add_f32_e32 v32, 1.0, v32
	v_exp_f32_e32 v28, v28
	v_mul_f32_e32 v33, 0xbfb8aa3b, v33
	v_mul_f32_e32 v122, 0x3f317217, v120
	v_fma_f32 v122, v120, s17, -v122
	v_fmac_f32_e32 v122, 0x3377d1cf, v120
	v_fmac_f32_e32 v122, 0x3f317217, v120
	v_cmp_lt_f32_e64 s[0:1], |v120|, s86
	v_add_f32_e32 v28, 1.0, v28
	v_exp_f32_e32 v33, v33
	v_cndmask_b32_e64 v120, v120, v122, s[0:1]
	v_cndmask_b32_e32 v122, 0, v224, vcc
	v_sub_f32_e32 v120, v120, v122
	v_pk_add_f32 v[122:123], v[138:139], 1.0 op_sel_hi:[1,0] neg_lo:[1,0] neg_hi:[1,0]
	v_mul_f32_e32 v29, 0xbfb8aa3b, v29
	v_fma_f32 v117, v138, v123, v139
	v_cmp_gt_f32_e32 vcc, s16, v117
	v_mul_f32_e32 v122, v122, v123
	v_add_f32_e32 v33, 1.0, v33
	v_cndmask_b32_e64 v121, 0, 32, vcc
	v_ldexp_f32 v117, v117, v121
	v_log_f32_e32 v117, v117
	v_exp_f32_e32 v29, v29
	v_mul_f32_e32 v22, 0xbfb8aa3b, v22
	v_exp_f32_e32 v22, v22
	v_mul_f32_e32 v121, 0x3f317217, v117
	v_fma_f32 v121, v117, s17, -v121
	v_fmac_f32_e32 v121, 0x3377d1cf, v117
	v_fmac_f32_e32 v121, 0x3f317217, v117
	v_cmp_lt_f32_e64 s[0:1], |v117|, s86
	v_add_f32_e32 v29, 1.0, v29
	v_mul_f32_e32 v18, 0xbfb8aa3b, v18
	v_cndmask_b32_e64 v117, v117, v121, s[0:1]
	v_cndmask_b32_e32 v121, 0, v224, vcc
	v_sub_f32_e32 v117, v117, v121
	v_fma_f32 v121, v130, v167, v131
	v_cmp_gt_f32_e32 vcc, s16, v121
	v_add_f32_e32 v22, 1.0, v22
	v_exp_f32_e32 v18, v18
	v_cndmask_b32_e64 v130, 0, 32, vcc
	v_ldexp_f32 v121, v121, v130
	v_log_f32_e32 v121, v121
	v_add_f32_e32 v18, 1.0, v18
	v_mul_f32_e32 v23, 0xbfb8aa3b, v23
	v_exp_f32_e32 v23, v23
	v_mul_f32_e32 v130, 0x3f317217, v121
	v_fma_f32 v130, v121, s17, -v130
	v_fmac_f32_e32 v130, 0x3377d1cf, v121
	v_fmac_f32_e32 v130, 0x3f317217, v121
	v_cmp_lt_f32_e64 s[0:1], |v121|, s86
	v_mul_f32_e32 v19, 0xbfb8aa3b, v19
	v_add_f32_e32 v23, 1.0, v23
	v_cndmask_b32_e64 v121, v121, v130, s[0:1]
	v_cndmask_b32_e32 v130, 0, v224, vcc
	v_sub_f32_e32 v121, v121, v130
	global_store_dwordx4 v[212:213], v[114:117], off offset:-3584 nt
	global_store_dwordx4 v[212:213], v[118:121], off offset:-3568 nt
	v_mul_f32_e32 v130, v166, v167
	v_cvt_pk_bf16_f32 v114, v128, v126
	v_cvt_pk_bf16_f32 v115, v124, v122
	v_cvt_pk_bf16_f32 v116, v132, v136
	v_cvt_pk_bf16_f32 v117, v134, v130
	global_store_dwordx4 v[214:215], v[114:117], off offset:256 nt
	v_rcp_f32_e32 v118, v106
	v_rcp_f32_e32 v120, v107
	v_or_b32_e32 v114, 16, v164
	v_ashrrev_i32_e32 v115, 31, v114
	v_lshlrev_b64 v[116:117], 12, v[114:115]
	v_rcp_f32_e32 v115, v110
	v_rcp_f32_e32 v122, v108
	v_rcp_f32_e32 v126, v109
	v_lshl_add_u64 v[116:117], s[12:13], 0, v[116:117]
	v_fma_f32 v106, v115, v193, v171
	v_cmp_gt_f32_e32 vcc, s16, v106
	v_lshl_add_u64 v[116:117], v[116:117], 0, v[168:169]
	v_sub_f32_e32 v115, 1.0, v115
	v_cndmask_b32_e64 v110, 0, 32, vcc
	v_ldexp_f32 v106, v106, v110
	v_log_f32_e32 v106, v106
	v_mul_f32_e32 v115, v115, v193
	v_exp_f32_e32 v19, v19
	v_mul_f32_e32 v24, 0xbfb8aa3b, v24
	v_mul_f32_e32 v110, 0x3f317217, v106
	v_fma_f32 v110, v106, s17, -v110
	v_fmac_f32_e32 v110, 0x3377d1cf, v106
	v_fmac_f32_e32 v110, 0x3f317217, v106
	v_cmp_lt_f32_e64 s[0:1], |v106|, s86
	v_add_f32_e32 v19, 1.0, v19
	v_exp_f32_e32 v24, v24
	v_cndmask_b32_e64 v106, v106, v110, s[0:1]
	v_cndmask_b32_e32 v110, 0, v224, vcc
	v_sub_f32_e32 v106, v106, v110
	v_fma_f32 v110, v118, v207, v185
	v_cmp_gt_f32_e32 vcc, s16, v110
	v_sub_f32_e32 v118, 1.0, v118
	v_mul_f32_e32 v118, v118, v207
	v_cndmask_b32_e64 v119, 0, 32, vcc
	v_ldexp_f32 v110, v110, v119
	v_log_f32_e32 v110, v110
	v_mul_f32_e32 v20, 0xbfb8aa3b, v20
	v_add_f32_e32 v24, 1.0, v24
	v_exp_f32_e32 v20, v20
	v_mul_f32_e32 v119, 0x3f317217, v110
	v_fma_f32 v119, v110, s17, -v119
	v_fmac_f32_e32 v119, 0x3377d1cf, v110
	v_fmac_f32_e32 v119, 0x3f317217, v110
	v_cmp_lt_f32_e64 s[0:1], |v110|, s86
	v_add_f32_e32 v20, 1.0, v20
	v_mul_f32_e32 v25, 0xbfb8aa3b, v25
	v_cndmask_b32_e64 v110, v110, v119, s[0:1]
	v_cndmask_b32_e32 v119, 0, v224, vcc
	v_sub_f32_e32 v110, v110, v119
	v_rcp_f32_e32 v119, v111
	v_exp_f32_e32 v25, v25
	v_mul_f32_e32 v21, 0xbfb8aa3b, v21
	v_exp_f32_e32 v21, v21
	v_fma_f32 v107, v119, v191, v173
	v_cmp_gt_f32_e32 vcc, s16, v107
	v_sub_f32_e32 v119, 1.0, v119
	v_mul_f32_e32 v119, v119, v191
	v_cndmask_b32_e64 v111, 0, 32, vcc
	v_ldexp_f32 v107, v107, v111
	v_log_f32_e32 v107, v107
	v_add_f32_e32 v25, 1.0, v25
	v_add_f32_e32 v21, 1.0, v21
	v_mul_f32_e32 v14, 0xbfb8aa3b, v14
	v_mul_f32_e32 v111, 0x3f317217, v107
	v_fma_f32 v111, v107, s17, -v111
	v_fmac_f32_e32 v111, 0x3377d1cf, v107
	v_fmac_f32_e32 v111, 0x3f317217, v107
	v_cmp_lt_f32_e64 s[0:1], |v107|, s86
	v_exp_f32_e32 v14, v14
	v_mul_f32_e32 v10, 0xbfb8aa3b, v10
	v_cndmask_b32_e64 v107, v107, v111, s[0:1]
	v_cndmask_b32_e32 v111, 0, v224, vcc
	v_sub_f32_e32 v107, v107, v111
	v_fma_f32 v111, v120, v205, v183
	v_cmp_gt_f32_e32 vcc, s16, v111
	v_sub_f32_e32 v120, 1.0, v120
	v_mul_f32_e32 v120, v120, v205
	v_cndmask_b32_e64 v121, 0, 32, vcc
	v_ldexp_f32 v111, v111, v121
	v_log_f32_e32 v111, v111
	v_add_f32_e32 v14, 1.0, v14
	v_exp_f32_e32 v10, v10
	v_mul_f32_e32 v15, 0xbfb8aa3b, v15
	v_mul_f32_e32 v121, 0x3f317217, v111
	v_fma_f32 v121, v111, s17, -v121
	v_fmac_f32_e32 v121, 0x3377d1cf, v111
	v_fmac_f32_e32 v121, 0x3f317217, v111
	v_cmp_lt_f32_e64 s[0:1], |v111|, s86
	v_add_f32_e32 v10, 1.0, v10
	v_exp_f32_e32 v15, v15
	v_cndmask_b32_e64 v111, v111, v121, s[0:1]
	v_cndmask_b32_e32 v121, 0, v224, vcc
	v_sub_f32_e32 v111, v111, v121
	v_rcp_f32_e32 v121, v112
	v_add_f32_e32 v15, 1.0, v15
	v_mul_f32_e32 v11, 0xbfb8aa3b, v11
	v_exp_f32_e32 v11, v11
	v_fma_f32 v108, v121, v137, v175
	v_cmp_gt_f32_e32 vcc, s16, v108
	v_sub_f32_e32 v121, 1.0, v121
	v_mul_f32_e32 v121, v121, v137
	v_cndmask_b32_e64 v112, 0, 32, vcc
	v_ldexp_f32 v108, v108, v112
	v_log_f32_e32 v108, v108
	v_add_f32_e32 v11, 1.0, v11
	v_mul_f32_e32 v16, 0xbfb8aa3b, v16
	v_exp_f32_e32 v16, v16
	v_mul_f32_e32 v112, 0x3f317217, v108
	v_fma_f32 v112, v108, s17, -v112
	v_fmac_f32_e32 v112, 0x3377d1cf, v108
	v_fmac_f32_e32 v112, 0x3f317217, v108
	v_cmp_lt_f32_e64 s[0:1], |v108|, s86
	v_add_f32_e32 v16, 1.0, v16
	v_mul_f32_e32 v12, 0xbfb8aa3b, v12
	v_cndmask_b32_e64 v108, v108, v112, s[0:1]
	v_cndmask_b32_e32 v112, 0, v224, vcc
	v_sub_f32_e32 v108, v108, v112
	v_fma_f32 v112, v122, v203, v181
	v_cmp_gt_f32_e32 vcc, s16, v112
	v_sub_f32_e32 v122, 1.0, v122
	v_mul_f32_e32 v122, v122, v203
	v_cndmask_b32_e64 v124, 0, 32, vcc
	v_ldexp_f32 v112, v112, v124
	v_log_f32_e32 v112, v112
	v_exp_f32_e32 v12, v12
	v_mul_f32_e32 v17, 0xbfb8aa3b, v17
	v_exp_f32_e32 v17, v17
	v_mul_f32_e32 v124, 0x3f317217, v112
	v_fma_f32 v124, v112, s17, -v124
	v_fmac_f32_e32 v124, 0x3377d1cf, v112
	v_fmac_f32_e32 v124, 0x3f317217, v112
	v_cmp_lt_f32_e64 s[0:1], |v112|, s86
	v_add_f32_e32 v12, 1.0, v12
	v_add_f32_e32 v17, 1.0, v17
	v_cndmask_b32_e64 v112, v112, v124, s[0:1]
	v_cndmask_b32_e32 v124, 0, v224, vcc
	v_sub_f32_e32 v112, v112, v124
	v_rcp_f32_e32 v124, v113
	v_mul_f32_e32 v13, 0xbfb8aa3b, v13
	v_exp_f32_e32 v13, v13
	v_mul_f32_e32 v6, 0xbfb8aa3b, v6
	v_fma_f32 v109, v124, v133, v177
	v_cmp_gt_f32_e32 vcc, s16, v109
	v_sub_f32_e32 v124, 1.0, v124
	v_mul_f32_e32 v124, v124, v133
	v_cndmask_b32_e64 v113, 0, 32, vcc
	v_ldexp_f32 v109, v109, v113
	v_log_f32_e32 v109, v109
	v_add_f32_e32 v13, 1.0, v13
	v_exp_f32_e32 v6, v6
	v_mul_f32_e32 v2, 0xbfb8aa3b, v2
	v_mul_f32_e32 v113, 0x3f317217, v109
	v_fma_f32 v113, v109, s17, -v113
	v_fmac_f32_e32 v113, 0x3377d1cf, v109
	v_fmac_f32_e32 v113, 0x3f317217, v109
	v_cmp_lt_f32_e64 s[0:1], |v109|, s86
	v_add_f32_e32 v6, 1.0, v6
	v_exp_f32_e32 v2, v2
	v_cndmask_b32_e64 v109, v109, v113, s[0:1]
	v_cndmask_b32_e32 v113, 0, v224, vcc
	v_sub_f32_e32 v109, v109, v113
	v_fma_f32 v113, v126, v201, v179
	v_cmp_gt_f32_e32 vcc, s16, v113
	v_sub_f32_e32 v126, 1.0, v126
	v_mul_f32_e32 v126, v126, v201
	v_cndmask_b32_e64 v128, 0, 32, vcc
	v_ldexp_f32 v113, v113, v128
	v_log_f32_e32 v113, v113
	v_add_f32_e32 v2, 1.0, v2
	v_mul_f32_e32 v7, 0xbfb8aa3b, v7
	v_exp_f32_e32 v7, v7
	v_mul_f32_e32 v128, 0x3f317217, v113
	v_fma_f32 v128, v113, s17, -v128
	v_fmac_f32_e32 v128, 0x3377d1cf, v113
	v_fmac_f32_e32 v128, 0x3f317217, v113
	v_cmp_lt_f32_e64 s[0:1], |v113|, s86
	v_add_f32_e32 v7, 1.0, v7
	v_mul_f32_e32 v3, 0xbfb8aa3b, v3
	v_cndmask_b32_e64 v113, v113, v128, s[0:1]
	v_cndmask_b32_e32 v128, 0, v224, vcc
	v_sub_f32_e32 v113, v113, v128
	global_store_dwordx4 v[116:117], v[106:109], off offset:-4096 nt
	global_store_dwordx4 v[116:117], v[110:113], off offset:-4080 nt
	v_exp_f32_e32 v3, v3
	v_mad_i64_i32 v[106:107], s[0:1], v114, s8, v[208:209]
	v_cvt_pk_bf16_f32 v108, v115, v119
	v_lshl_add_u64 v[106:107], v[106:107], 0, v[210:211]
	v_cvt_pk_bf16_f32 v109, v121, v124
	v_cvt_pk_bf16_f32 v110, v118, v120
	v_cvt_pk_bf16_f32 v111, v122, v126
	global_store_dwordx4 v[106:107], v[108:111], off nt
	v_rcp_f32_e32 v113, v100
	v_rcp_f32_e32 v115, v101
	v_rcp_f32_e32 v108, v102
	v_rcp_f32_e32 v109, v98
	v_rcp_f32_e32 v111, v99
	v_add_f32_e32 v3, 1.0, v3
	v_fma_f32 v98, v108, v129, v189
	v_cmp_gt_f32_e32 vcc, s16, v98
	v_sub_f32_e32 v108, 1.0, v108
	v_mul_f32_e32 v108, v108, v129
	v_cndmask_b32_e64 v102, 0, 32, vcc
	v_ldexp_f32 v98, v98, v102
	v_log_f32_e32 v98, v98
	v_mul_f32_e32 v8, 0xbfb8aa3b, v8
	v_exp_f32_e32 v8, v8
	v_mul_f32_e32 v4, 0xbfb8aa3b, v4
	v_mul_f32_e32 v102, 0x3f317217, v98
	v_fma_f32 v102, v98, s17, -v102
	v_fmac_f32_e32 v102, 0x3377d1cf, v98
	v_fmac_f32_e32 v102, 0x3f317217, v98
	v_cmp_lt_f32_e64 s[0:1], |v98|, s86
	v_add_f32_e32 v8, 1.0, v8
	v_exp_f32_e32 v4, v4
	v_cndmask_b32_e64 v98, v98, v102, s[0:1]
	v_cndmask_b32_e32 v102, 0, v224, vcc
	v_sub_f32_e32 v98, v98, v102
	v_fma_f32 v102, v109, v199, v145
	v_cmp_gt_f32_e32 vcc, s16, v102
	v_sub_f32_e32 v109, 1.0, v109
	v_mul_f32_e32 v109, v109, v199
	v_cndmask_b32_e64 v110, 0, 32, vcc
	v_ldexp_f32 v102, v102, v110
	v_log_f32_e32 v102, v102
	v_add_f32_e32 v4, 1.0, v4
	v_mul_f32_e32 v9, 0xbfb8aa3b, v9
	v_exp_f32_e32 v9, v9
	v_mul_f32_e32 v110, 0x3f317217, v102
	v_fma_f32 v110, v102, s17, -v110
	v_fmac_f32_e32 v110, 0x3377d1cf, v102
	v_fmac_f32_e32 v110, 0x3f317217, v102
	v_cmp_lt_f32_e64 s[0:1], |v102|, s86
	v_add_f32_e32 v9, 1.0, v9
	v_mul_f32_e32 v5, 0xbfb8aa3b, v5
	v_cndmask_b32_e64 v102, v102, v110, s[0:1]
	v_cndmask_b32_e32 v110, 0, v224, vcc
	v_sub_f32_e32 v102, v102, v110
	v_rcp_f32_e32 v110, v103
	v_exp_f32_e32 v5, v5
	v_readlane_b32 s53, v254, 12
	v_readlane_b32 s54, v254, 13
	v_fma_f32 v99, v110, v127, v187
	v_cmp_gt_f32_e32 vcc, s16, v99
	v_sub_f32_e32 v110, 1.0, v110
	v_mul_f32_e32 v110, v110, v127
	v_cndmask_b32_e64 v103, 0, 32, vcc
	v_ldexp_f32 v99, v99, v103
	v_log_f32_e32 v99, v99
	v_add_f32_e32 v5, 1.0, v5
	v_readlane_b32 s55, v254, 14
	v_readlane_b32 s56, v254, 15
	v_mul_f32_e32 v103, 0x3f317217, v99
	v_fma_f32 v103, v99, s17, -v103
	v_fmac_f32_e32 v103, 0x3377d1cf, v99
	v_fmac_f32_e32 v103, 0x3f317217, v99
	v_cmp_lt_f32_e64 s[0:1], |v99|, s86
	v_readlane_b32 s57, v254, 16
	v_readlane_b32 s58, v254, 17
	v_cndmask_b32_e64 v99, v99, v103, s[0:1]
	v_cndmask_b32_e32 v103, 0, v224, vcc
	v_sub_f32_e32 v99, v99, v103
	v_fma_f32 v103, v111, v197, v141
	v_cmp_gt_f32_e32 vcc, s16, v103
	v_sub_f32_e32 v111, 1.0, v111
	v_mul_f32_e32 v111, v111, v197
	v_cndmask_b32_e64 v112, 0, 32, vcc
	v_ldexp_f32 v103, v103, v112
	v_log_f32_e32 v103, v103
	v_readlane_b32 s59, v254, 18
	v_readlane_b32 s60, v254, 19
	v_readlane_b32 s61, v254, 20
	v_mul_f32_e32 v112, 0x3f317217, v103
	v_fma_f32 v112, v103, s17, -v112
	v_fmac_f32_e32 v112, 0x3377d1cf, v103
	v_fmac_f32_e32 v112, 0x3f317217, v103
	v_cmp_lt_f32_e64 s[0:1], |v103|, s86
	v_readlane_b32 s64, v254, 23
	v_readlane_b32 s65, v254, 24
	v_cndmask_b32_e64 v103, v103, v112, s[0:1]
	v_cndmask_b32_e32 v112, 0, v224, vcc
	v_sub_f32_e32 v103, v103, v112
	v_rcp_f32_e32 v112, v104
	v_readlane_b32 s66, v254, 25
	v_readlane_b32 s67, v254, 26
	v_fma_f32 v100, v112, v125, v143
	v_cmp_gt_f32_e32 vcc, s16, v100
	v_sub_f32_e32 v112, 1.0, v112
	v_mul_f32_e32 v112, v112, v125
	v_cndmask_b32_e64 v104, 0, 32, vcc
	v_ldexp_f32 v100, v100, v104
	v_log_f32_e32 v100, v100
	s_nop 0
	v_mul_f32_e32 v104, 0x3f317217, v100
	v_fma_f32 v104, v100, s17, -v104
	v_fmac_f32_e32 v104, 0x3377d1cf, v100
	v_fmac_f32_e32 v104, 0x3f317217, v100
	v_cmp_lt_f32_e64 s[0:1], |v100|, s86
	s_nop 1
	v_cndmask_b32_e64 v100, v100, v104, s[0:1]
	v_cndmask_b32_e32 v104, 0, v224, vcc
	v_sub_f32_e32 v100, v100, v104
	v_fma_f32 v104, v113, v195, v135
	v_cmp_gt_f32_e32 vcc, s16, v104
	v_sub_f32_e32 v113, 1.0, v113
	v_mul_f32_e32 v113, v113, v195
	v_cndmask_b32_e64 v114, 0, 32, vcc
	v_ldexp_f32 v104, v104, v114
	v_log_f32_e32 v104, v104
	s_nop 0
	v_mul_f32_e32 v114, 0x3f317217, v104
	v_fma_f32 v114, v104, s17, -v114
	v_fmac_f32_e32 v114, 0x3377d1cf, v104
	v_fmac_f32_e32 v114, 0x3f317217, v104
	v_cmp_lt_f32_e64 s[0:1], |v104|, s86
	s_nop 1
	v_cndmask_b32_e64 v104, v104, v114, s[0:1]
	v_cndmask_b32_e32 v114, 0, v224, vcc
	v_sub_f32_e32 v104, v104, v114
	v_rcp_f32_e32 v114, v105
	s_nop 0
	v_fma_f32 v101, v114, v123, v139
	v_cmp_gt_f32_e32 vcc, s16, v101
	v_sub_f32_e32 v114, 1.0, v114
	v_mul_f32_e32 v114, v114, v123
	v_cndmask_b32_e64 v105, 0, 32, vcc
	v_ldexp_f32 v101, v101, v105
	v_log_f32_e32 v101, v101
	s_nop 0
	v_mul_f32_e32 v105, 0x3f317217, v101
	v_fma_f32 v105, v101, s17, -v105
	v_fmac_f32_e32 v105, 0x3377d1cf, v101
	v_fmac_f32_e32 v105, 0x3f317217, v101
	v_cmp_lt_f32_e64 s[0:1], |v101|, s86
	s_nop 1
	v_cndmask_b32_e64 v101, v101, v105, s[0:1]
	v_cndmask_b32_e32 v105, 0, v224, vcc
	v_sub_f32_e32 v101, v101, v105
	v_fma_f32 v105, v115, v167, v131
	v_cmp_gt_f32_e32 vcc, s16, v105
	v_sub_f32_e32 v115, 1.0, v115
	v_mul_f32_e32 v115, v115, v167
	v_cndmask_b32_e64 v118, 0, 32, vcc
	v_ldexp_f32 v105, v105, v118
	v_log_f32_e32 v105, v105
	s_nop 0
	v_mul_f32_e32 v118, 0x3f317217, v105
	v_fma_f32 v118, v105, s17, -v118
	v_fmac_f32_e32 v118, 0x3377d1cf, v105
	v_fmac_f32_e32 v118, 0x3f317217, v105
	v_cmp_lt_f32_e64 s[0:1], |v105|, s86
	s_nop 1
	v_cndmask_b32_e64 v105, v105, v118, s[0:1]
	v_cndmask_b32_e32 v118, 0, v224, vcc
	v_sub_f32_e32 v105, v105, v118
	global_store_dwordx4 v[116:117], v[98:101], off offset:-3584 nt
	global_store_dwordx4 v[116:117], v[102:105], off offset:-3568 nt
	s_nop 0
	v_cvt_pk_bf16_f32 v98, v108, v110
	v_cvt_pk_bf16_f32 v99, v112, v114
	v_cvt_pk_bf16_f32 v100, v109, v111
	v_cvt_pk_bf16_f32 v101, v113, v115
	global_store_dwordx4 v[106:107], v[98:101], off offset:256 nt
	v_rcp_f32_e32 v102, v90
	v_rcp_f32_e32 v104, v91
	v_or_b32_e32 v98, 32, v164
	v_ashrrev_i32_e32 v99, 31, v98
	v_lshlrev_b64 v[100:101], 12, v[98:99]
	v_rcp_f32_e32 v99, v94
	v_rcp_f32_e32 v106, v92
	v_rcp_f32_e32 v108, v93
	v_lshl_add_u64 v[100:101], s[12:13], 0, v[100:101]
	v_fma_f32 v90, v99, v193, v171
	v_cmp_gt_f32_e32 vcc, s16, v90
	v_lshl_add_u64 v[100:101], v[100:101], 0, v[168:169]
	v_sub_f32_e32 v99, 1.0, v99
	v_cndmask_b32_e64 v94, 0, 32, vcc
	v_ldexp_f32 v90, v90, v94
	v_log_f32_e32 v90, v90
	v_mul_f32_e32 v99, v99, v193
	v_mul_f32_e32 v94, 0x3f317217, v90
	v_fma_f32 v94, v90, s17, -v94
	v_fmac_f32_e32 v94, 0x3377d1cf, v90
	v_fmac_f32_e32 v94, 0x3f317217, v90
	v_cmp_lt_f32_e64 s[0:1], |v90|, s86
	s_nop 1
	v_cndmask_b32_e64 v90, v90, v94, s[0:1]
	v_cndmask_b32_e32 v94, 0, v224, vcc
	v_sub_f32_e32 v90, v90, v94
	v_fma_f32 v94, v102, v207, v185
	v_cmp_gt_f32_e32 vcc, s16, v94
	v_sub_f32_e32 v102, 1.0, v102
	v_mul_f32_e32 v102, v102, v207
	v_cndmask_b32_e64 v103, 0, 32, vcc
	v_ldexp_f32 v94, v94, v103
	v_log_f32_e32 v94, v94
	s_nop 0
	v_mul_f32_e32 v103, 0x3f317217, v94
	v_fma_f32 v103, v94, s17, -v103
	v_fmac_f32_e32 v103, 0x3377d1cf, v94
	v_fmac_f32_e32 v103, 0x3f317217, v94
	v_cmp_lt_f32_e64 s[0:1], |v94|, s86
	s_nop 1
	v_cndmask_b32_e64 v94, v94, v103, s[0:1]
	v_cndmask_b32_e32 v103, 0, v224, vcc
	v_sub_f32_e32 v94, v94, v103
	v_rcp_f32_e32 v103, v95
	s_nop 0
	v_fma_f32 v91, v103, v191, v173
	v_cmp_gt_f32_e32 vcc, s16, v91
	v_sub_f32_e32 v103, 1.0, v103
	v_mul_f32_e32 v103, v103, v191
	v_cndmask_b32_e64 v95, 0, 32, vcc
	v_ldexp_f32 v91, v91, v95
	v_log_f32_e32 v91, v91
	s_nop 0
	v_mul_f32_e32 v95, 0x3f317217, v91
	v_fma_f32 v95, v91, s17, -v95
	v_fmac_f32_e32 v95, 0x3377d1cf, v91
	v_fmac_f32_e32 v95, 0x3f317217, v91
	v_cmp_lt_f32_e64 s[0:1], |v91|, s86
	s_nop 1
	v_cndmask_b32_e64 v91, v91, v95, s[0:1]
	v_cndmask_b32_e32 v95, 0, v224, vcc
	v_sub_f32_e32 v91, v91, v95
	v_fma_f32 v95, v104, v205, v183
	v_cmp_gt_f32_e32 vcc, s16, v95
	v_sub_f32_e32 v104, 1.0, v104
	v_mul_f32_e32 v104, v104, v205
	v_cndmask_b32_e64 v105, 0, 32, vcc
	v_ldexp_f32 v95, v95, v105
	v_log_f32_e32 v95, v95
	s_nop 0
	v_mul_f32_e32 v105, 0x3f317217, v95
	v_fma_f32 v105, v95, s17, -v105
	v_fmac_f32_e32 v105, 0x3377d1cf, v95
	v_fmac_f32_e32 v105, 0x3f317217, v95
	v_cmp_lt_f32_e64 s[0:1], |v95|, s86
	s_nop 1
	v_cndmask_b32_e64 v95, v95, v105, s[0:1]
	v_cndmask_b32_e32 v105, 0, v224, vcc
	v_sub_f32_e32 v95, v95, v105
	v_rcp_f32_e32 v105, v96
	s_nop 0
	v_fma_f32 v92, v105, v137, v175
	v_cmp_gt_f32_e32 vcc, s16, v92
	v_sub_f32_e32 v105, 1.0, v105
	v_mul_f32_e32 v105, v105, v137
	v_cndmask_b32_e64 v96, 0, 32, vcc
	v_ldexp_f32 v92, v92, v96
	v_log_f32_e32 v92, v92
	s_nop 0
	v_mul_f32_e32 v96, 0x3f317217, v92
	v_fma_f32 v96, v92, s17, -v96
	v_fmac_f32_e32 v96, 0x3377d1cf, v92
	v_fmac_f32_e32 v96, 0x3f317217, v92
	v_cmp_lt_f32_e64 s[0:1], |v92|, s86
	s_nop 1
	v_cndmask_b32_e64 v92, v92, v96, s[0:1]
	v_cndmask_b32_e32 v96, 0, v224, vcc
	v_sub_f32_e32 v92, v92, v96
	v_fma_f32 v96, v106, v203, v181
	v_cmp_gt_f32_e32 vcc, s16, v96
	v_sub_f32_e32 v106, 1.0, v106
	v_mul_f32_e32 v106, v106, v203
	v_cndmask_b32_e64 v107, 0, 32, vcc
	v_ldexp_f32 v96, v96, v107
	v_log_f32_e32 v96, v96
	s_nop 0
	v_mul_f32_e32 v107, 0x3f317217, v96
	v_fma_f32 v107, v96, s17, -v107
	v_fmac_f32_e32 v107, 0x3377d1cf, v96
	v_fmac_f32_e32 v107, 0x3f317217, v96
	v_cmp_lt_f32_e64 s[0:1], |v96|, s86
	s_nop 1
	v_cndmask_b32_e64 v96, v96, v107, s[0:1]
	v_cndmask_b32_e32 v107, 0, v224, vcc
	v_sub_f32_e32 v96, v96, v107
	v_rcp_f32_e32 v107, v97
	s_nop 0
	v_fma_f32 v93, v107, v133, v177
	v_cmp_gt_f32_e32 vcc, s16, v93
	v_sub_f32_e32 v107, 1.0, v107
	v_mul_f32_e32 v107, v107, v133
	v_cndmask_b32_e64 v97, 0, 32, vcc
	v_ldexp_f32 v93, v93, v97
	v_log_f32_e32 v93, v93
	s_nop 0
	v_mul_f32_e32 v97, 0x3f317217, v93
	v_fma_f32 v97, v93, s17, -v97
	v_fmac_f32_e32 v97, 0x3377d1cf, v93
	v_fmac_f32_e32 v97, 0x3f317217, v93
	v_cmp_lt_f32_e64 s[0:1], |v93|, s86
	s_nop 1
	v_cndmask_b32_e64 v93, v93, v97, s[0:1]
	v_cndmask_b32_e32 v97, 0, v224, vcc
	v_sub_f32_e32 v93, v93, v97
	v_fma_f32 v97, v108, v201, v179
	v_cmp_gt_f32_e32 vcc, s16, v97
	v_sub_f32_e32 v108, 1.0, v108
	v_mul_f32_e32 v108, v108, v201
	v_cndmask_b32_e64 v109, 0, 32, vcc
	v_ldexp_f32 v97, v97, v109
	v_log_f32_e32 v97, v97
	s_nop 0
	v_mul_f32_e32 v109, 0x3f317217, v97
	v_fma_f32 v109, v97, s17, -v109
	v_fmac_f32_e32 v109, 0x3377d1cf, v97
	v_fmac_f32_e32 v109, 0x3f317217, v97
	v_cmp_lt_f32_e64 s[0:1], |v97|, s86
	s_nop 1
	v_cndmask_b32_e64 v97, v97, v109, s[0:1]
	v_cndmask_b32_e32 v109, 0, v224, vcc
	v_sub_f32_e32 v97, v97, v109
	global_store_dwordx4 v[100:101], v[90:93], off offset:-4096 nt
	global_store_dwordx4 v[100:101], v[94:97], off offset:-4080 nt
	s_nop 0
	v_mad_i64_i32 v[90:91], s[0:1], v98, s8, v[208:209]
	v_cvt_pk_bf16_f32 v92, v99, v103
	v_lshl_add_u64 v[90:91], v[90:91], 0, v[210:211]
	v_cvt_pk_bf16_f32 v93, v105, v107
	v_cvt_pk_bf16_f32 v94, v102, v104
	v_cvt_pk_bf16_f32 v95, v106, v108
	global_store_dwordx4 v[90:91], v[92:95], off nt
	v_rcp_f32_e32 v97, v84
	v_rcp_f32_e32 v99, v85
	v_rcp_f32_e32 v92, v86
	v_rcp_f32_e32 v93, v82
	v_rcp_f32_e32 v95, v83
	v_fma_f32 v82, v92, v129, v189
	v_cmp_gt_f32_e32 vcc, s16, v82
	v_sub_f32_e32 v92, 1.0, v92
	v_mul_f32_e32 v92, v92, v129
	v_cndmask_b32_e64 v86, 0, 32, vcc
	v_ldexp_f32 v82, v82, v86
	v_log_f32_e32 v82, v82
	s_nop 0
	v_mul_f32_e32 v86, 0x3f317217, v82
	v_fma_f32 v86, v82, s17, -v86
	v_fmac_f32_e32 v86, 0x3377d1cf, v82
	v_fmac_f32_e32 v86, 0x3f317217, v82
	v_cmp_lt_f32_e64 s[0:1], |v82|, s86
	s_nop 1
	v_cndmask_b32_e64 v82, v82, v86, s[0:1]
	v_cndmask_b32_e32 v86, 0, v224, vcc
	v_sub_f32_e32 v82, v82, v86
	v_fma_f32 v86, v93, v199, v145
	v_cmp_gt_f32_e32 vcc, s16, v86
	v_sub_f32_e32 v93, 1.0, v93
	v_mul_f32_e32 v93, v93, v199
	v_cndmask_b32_e64 v94, 0, 32, vcc
	v_ldexp_f32 v86, v86, v94
	v_log_f32_e32 v86, v86
	s_nop 0
	v_mul_f32_e32 v94, 0x3f317217, v86
	v_fma_f32 v94, v86, s17, -v94
	v_fmac_f32_e32 v94, 0x3377d1cf, v86
	v_fmac_f32_e32 v94, 0x3f317217, v86
	v_cmp_lt_f32_e64 s[0:1], |v86|, s86
	s_nop 1
	v_cndmask_b32_e64 v86, v86, v94, s[0:1]
	v_cndmask_b32_e32 v94, 0, v224, vcc
	v_sub_f32_e32 v86, v86, v94
	v_rcp_f32_e32 v94, v87
	s_nop 0
	v_fma_f32 v83, v94, v127, v187
	v_cmp_gt_f32_e32 vcc, s16, v83
	v_sub_f32_e32 v94, 1.0, v94
	v_mul_f32_e32 v94, v94, v127
	v_cndmask_b32_e64 v87, 0, 32, vcc
	v_ldexp_f32 v83, v83, v87
	v_log_f32_e32 v83, v83
	s_nop 0
	v_mul_f32_e32 v87, 0x3f317217, v83
	v_fma_f32 v87, v83, s17, -v87
	v_fmac_f32_e32 v87, 0x3377d1cf, v83
	v_fmac_f32_e32 v87, 0x3f317217, v83
	v_cmp_lt_f32_e64 s[0:1], |v83|, s86
	s_nop 1
	v_cndmask_b32_e64 v83, v83, v87, s[0:1]
	v_cndmask_b32_e32 v87, 0, v224, vcc
	v_sub_f32_e32 v83, v83, v87
	v_fma_f32 v87, v95, v197, v141
	v_cmp_gt_f32_e32 vcc, s16, v87
	v_sub_f32_e32 v95, 1.0, v95
	v_mul_f32_e32 v95, v95, v197
	v_cndmask_b32_e64 v96, 0, 32, vcc
	v_ldexp_f32 v87, v87, v96
	v_log_f32_e32 v87, v87
	s_nop 0
	v_mul_f32_e32 v96, 0x3f317217, v87
	v_fma_f32 v96, v87, s17, -v96
	v_fmac_f32_e32 v96, 0x3377d1cf, v87
	v_fmac_f32_e32 v96, 0x3f317217, v87
	v_cmp_lt_f32_e64 s[0:1], |v87|, s86
	s_nop 1
	v_cndmask_b32_e64 v87, v87, v96, s[0:1]
	v_cndmask_b32_e32 v96, 0, v224, vcc
	v_sub_f32_e32 v87, v87, v96
	v_rcp_f32_e32 v96, v88
	s_nop 0
	v_fma_f32 v84, v96, v125, v143
	v_cmp_gt_f32_e32 vcc, s16, v84
	v_sub_f32_e32 v96, 1.0, v96
	v_mul_f32_e32 v96, v96, v125
	v_cndmask_b32_e64 v88, 0, 32, vcc
	v_ldexp_f32 v84, v84, v88
	v_log_f32_e32 v84, v84
	s_nop 0
	v_mul_f32_e32 v88, 0x3f317217, v84
	v_fma_f32 v88, v84, s17, -v88
	v_fmac_f32_e32 v88, 0x3377d1cf, v84
	v_fmac_f32_e32 v88, 0x3f317217, v84
	v_cmp_lt_f32_e64 s[0:1], |v84|, s86
	s_nop 1
	v_cndmask_b32_e64 v84, v84, v88, s[0:1]
	v_cndmask_b32_e32 v88, 0, v224, vcc
	v_sub_f32_e32 v84, v84, v88
	v_fma_f32 v88, v97, v195, v135
	v_cmp_gt_f32_e32 vcc, s16, v88
	v_sub_f32_e32 v97, 1.0, v97
	v_mul_f32_e32 v97, v97, v195
	v_cndmask_b32_e64 v98, 0, 32, vcc
	v_ldexp_f32 v88, v88, v98
	v_log_f32_e32 v88, v88
	s_nop 0
	v_mul_f32_e32 v98, 0x3f317217, v88
	v_fma_f32 v98, v88, s17, -v98
	v_fmac_f32_e32 v98, 0x3377d1cf, v88
	v_fmac_f32_e32 v98, 0x3f317217, v88
	v_cmp_lt_f32_e64 s[0:1], |v88|, s86
	s_nop 1
	v_cndmask_b32_e64 v88, v88, v98, s[0:1]
	v_cndmask_b32_e32 v98, 0, v224, vcc
	v_sub_f32_e32 v88, v88, v98
	v_rcp_f32_e32 v98, v89
	s_nop 0
	v_fma_f32 v85, v98, v123, v139
	v_cmp_gt_f32_e32 vcc, s16, v85
	v_sub_f32_e32 v98, 1.0, v98
	v_mul_f32_e32 v98, v98, v123
	v_cndmask_b32_e64 v89, 0, 32, vcc
	v_ldexp_f32 v85, v85, v89
	v_log_f32_e32 v85, v85
	s_nop 0
	v_mul_f32_e32 v89, 0x3f317217, v85
	v_fma_f32 v89, v85, s17, -v89
	v_fmac_f32_e32 v89, 0x3377d1cf, v85
	v_fmac_f32_e32 v89, 0x3f317217, v85
	v_cmp_lt_f32_e64 s[0:1], |v85|, s86
	s_nop 1
	v_cndmask_b32_e64 v85, v85, v89, s[0:1]
	v_cndmask_b32_e32 v89, 0, v224, vcc
	v_sub_f32_e32 v85, v85, v89
	v_fma_f32 v89, v99, v167, v131
	v_cmp_gt_f32_e32 vcc, s16, v89
	v_sub_f32_e32 v99, 1.0, v99
	v_mul_f32_e32 v99, v99, v167
	v_cndmask_b32_e64 v102, 0, 32, vcc
	v_ldexp_f32 v89, v89, v102
	v_log_f32_e32 v89, v89
	s_nop 0
	v_mul_f32_e32 v102, 0x3f317217, v89
	v_fma_f32 v102, v89, s17, -v102
	v_fmac_f32_e32 v102, 0x3377d1cf, v89
	v_fmac_f32_e32 v102, 0x3f317217, v89
	v_cmp_lt_f32_e64 s[0:1], |v89|, s86
	s_nop 1
	v_cndmask_b32_e64 v89, v89, v102, s[0:1]
	v_cndmask_b32_e32 v102, 0, v224, vcc
	v_sub_f32_e32 v89, v89, v102
	global_store_dwordx4 v[100:101], v[82:85], off offset:-3584 nt
	global_store_dwordx4 v[100:101], v[86:89], off offset:-3568 nt
	s_nop 0
	v_cvt_pk_bf16_f32 v82, v92, v94
	v_cvt_pk_bf16_f32 v83, v96, v98
	v_cvt_pk_bf16_f32 v84, v93, v95
	v_cvt_pk_bf16_f32 v85, v97, v99
	global_store_dwordx4 v[90:91], v[82:85], off offset:256 nt
	v_rcp_f32_e32 v86, v74
	v_rcp_f32_e32 v88, v75
	v_or_b32_e32 v82, 48, v164
	v_ashrrev_i32_e32 v83, 31, v82
	v_lshlrev_b64 v[84:85], 12, v[82:83]
	v_rcp_f32_e32 v83, v78
	v_rcp_f32_e32 v90, v76
	v_rcp_f32_e32 v92, v77
	v_lshl_add_u64 v[84:85], s[12:13], 0, v[84:85]
	v_fma_f32 v74, v83, v193, v171
	v_cmp_gt_f32_e32 vcc, s16, v74
	v_lshl_add_u64 v[84:85], v[84:85], 0, v[168:169]
	v_sub_f32_e32 v83, 1.0, v83
	v_cndmask_b32_e64 v78, 0, 32, vcc
	v_ldexp_f32 v74, v74, v78
	v_log_f32_e32 v74, v74
	v_mul_f32_e32 v83, v83, v193
	v_mul_f32_e32 v78, 0x3f317217, v74
	v_fma_f32 v78, v74, s17, -v78
	v_fmac_f32_e32 v78, 0x3377d1cf, v74
	v_fmac_f32_e32 v78, 0x3f317217, v74
	v_cmp_lt_f32_e64 s[0:1], |v74|, s86
	s_nop 1
	v_cndmask_b32_e64 v74, v74, v78, s[0:1]
	v_cndmask_b32_e32 v78, 0, v224, vcc
	v_sub_f32_e32 v74, v74, v78
	v_fma_f32 v78, v86, v207, v185
	v_cmp_gt_f32_e32 vcc, s16, v78
	v_sub_f32_e32 v86, 1.0, v86
	v_mul_f32_e32 v86, v86, v207
	v_cndmask_b32_e64 v87, 0, 32, vcc
	v_ldexp_f32 v78, v78, v87
	v_log_f32_e32 v78, v78
	s_nop 0
	v_mul_f32_e32 v87, 0x3f317217, v78
	v_fma_f32 v87, v78, s17, -v87
	v_fmac_f32_e32 v87, 0x3377d1cf, v78
	v_fmac_f32_e32 v87, 0x3f317217, v78
	v_cmp_lt_f32_e64 s[0:1], |v78|, s86
	s_nop 1
	v_cndmask_b32_e64 v78, v78, v87, s[0:1]
	v_cndmask_b32_e32 v87, 0, v224, vcc
	v_sub_f32_e32 v78, v78, v87
	v_rcp_f32_e32 v87, v79
	s_nop 0
	v_fma_f32 v75, v87, v191, v173
	v_cmp_gt_f32_e32 vcc, s16, v75
	v_sub_f32_e32 v87, 1.0, v87
	v_mul_f32_e32 v87, v87, v191
	v_cndmask_b32_e64 v79, 0, 32, vcc
	v_ldexp_f32 v75, v75, v79
	v_log_f32_e32 v75, v75
	s_nop 0
	v_mul_f32_e32 v79, 0x3f317217, v75
	v_fma_f32 v79, v75, s17, -v79
	v_fmac_f32_e32 v79, 0x3377d1cf, v75
	v_fmac_f32_e32 v79, 0x3f317217, v75
	v_cmp_lt_f32_e64 s[0:1], |v75|, s86
	s_nop 1
	v_cndmask_b32_e64 v75, v75, v79, s[0:1]
	v_cndmask_b32_e32 v79, 0, v224, vcc
	v_sub_f32_e32 v75, v75, v79
	v_fma_f32 v79, v88, v205, v183
	v_cmp_gt_f32_e32 vcc, s16, v79
	v_sub_f32_e32 v88, 1.0, v88
	v_mul_f32_e32 v88, v88, v205
	v_cndmask_b32_e64 v89, 0, 32, vcc
	v_ldexp_f32 v79, v79, v89
	v_log_f32_e32 v79, v79
	s_nop 0
	v_mul_f32_e32 v89, 0x3f317217, v79
	v_fma_f32 v89, v79, s17, -v89
	v_fmac_f32_e32 v89, 0x3377d1cf, v79
	v_fmac_f32_e32 v89, 0x3f317217, v79
	v_cmp_lt_f32_e64 s[0:1], |v79|, s86
	s_nop 1
	v_cndmask_b32_e64 v79, v79, v89, s[0:1]
	v_cndmask_b32_e32 v89, 0, v224, vcc
	v_sub_f32_e32 v79, v79, v89
	v_rcp_f32_e32 v89, v80
	s_nop 0
	v_fma_f32 v76, v89, v137, v175
	v_cmp_gt_f32_e32 vcc, s16, v76
	v_sub_f32_e32 v89, 1.0, v89
	v_mul_f32_e32 v89, v89, v137
	v_cndmask_b32_e64 v80, 0, 32, vcc
	v_ldexp_f32 v76, v76, v80
	v_log_f32_e32 v76, v76
	s_nop 0
	v_mul_f32_e32 v80, 0x3f317217, v76
	v_fma_f32 v80, v76, s17, -v80
	v_fmac_f32_e32 v80, 0x3377d1cf, v76
	v_fmac_f32_e32 v80, 0x3f317217, v76
	v_cmp_lt_f32_e64 s[0:1], |v76|, s86
	s_nop 1
	v_cndmask_b32_e64 v76, v76, v80, s[0:1]
	v_cndmask_b32_e32 v80, 0, v224, vcc
	v_sub_f32_e32 v76, v76, v80
	v_fma_f32 v80, v90, v203, v181
	v_cmp_gt_f32_e32 vcc, s16, v80
	v_sub_f32_e32 v90, 1.0, v90
	v_mul_f32_e32 v90, v90, v203
	v_cndmask_b32_e64 v91, 0, 32, vcc
	v_ldexp_f32 v80, v80, v91
	v_log_f32_e32 v80, v80
	s_nop 0
	v_mul_f32_e32 v91, 0x3f317217, v80
	v_fma_f32 v91, v80, s17, -v91
	v_fmac_f32_e32 v91, 0x3377d1cf, v80
	v_fmac_f32_e32 v91, 0x3f317217, v80
	v_cmp_lt_f32_e64 s[0:1], |v80|, s86
	s_nop 1
	v_cndmask_b32_e64 v80, v80, v91, s[0:1]
	v_cndmask_b32_e32 v91, 0, v224, vcc
	v_sub_f32_e32 v80, v80, v91
	v_rcp_f32_e32 v91, v81
	s_nop 0
	v_fma_f32 v77, v91, v133, v177
	v_cmp_gt_f32_e32 vcc, s16, v77
	v_sub_f32_e32 v91, 1.0, v91
	v_mul_f32_e32 v91, v91, v133
	v_cndmask_b32_e64 v81, 0, 32, vcc
	v_ldexp_f32 v77, v77, v81
	v_log_f32_e32 v77, v77
	s_nop 0
	v_mul_f32_e32 v81, 0x3f317217, v77
	v_fma_f32 v81, v77, s17, -v81
	v_fmac_f32_e32 v81, 0x3377d1cf, v77
	v_fmac_f32_e32 v81, 0x3f317217, v77
	v_cmp_lt_f32_e64 s[0:1], |v77|, s86
	s_nop 1
	v_cndmask_b32_e64 v77, v77, v81, s[0:1]
	v_cndmask_b32_e32 v81, 0, v224, vcc
	v_sub_f32_e32 v77, v77, v81
	v_fma_f32 v81, v92, v201, v179
	v_cmp_gt_f32_e32 vcc, s16, v81
	v_sub_f32_e32 v92, 1.0, v92
	v_mul_f32_e32 v92, v92, v201
	v_cndmask_b32_e64 v93, 0, 32, vcc
	v_ldexp_f32 v81, v81, v93
	v_log_f32_e32 v81, v81
	s_nop 0
	v_mul_f32_e32 v93, 0x3f317217, v81
	v_fma_f32 v93, v81, s17, -v93
	v_fmac_f32_e32 v93, 0x3377d1cf, v81
	v_fmac_f32_e32 v93, 0x3f317217, v81
	v_cmp_lt_f32_e64 s[0:1], |v81|, s86
	s_nop 1
	v_cndmask_b32_e64 v81, v81, v93, s[0:1]
	v_cndmask_b32_e32 v93, 0, v224, vcc
	v_sub_f32_e32 v81, v81, v93
	global_store_dwordx4 v[84:85], v[74:77], off offset:-4096 nt
	global_store_dwordx4 v[84:85], v[78:81], off offset:-4080 nt
	s_nop 0
	v_mad_i64_i32 v[74:75], s[0:1], v82, s8, v[208:209]
	v_cvt_pk_bf16_f32 v76, v83, v87
	v_lshl_add_u64 v[74:75], v[74:75], 0, v[210:211]
	v_cvt_pk_bf16_f32 v77, v89, v91
	v_cvt_pk_bf16_f32 v78, v86, v88
	v_cvt_pk_bf16_f32 v79, v90, v92
	global_store_dwordx4 v[74:75], v[76:79], off nt
	v_rcp_f32_e32 v81, v68
	v_rcp_f32_e32 v83, v69
	v_rcp_f32_e32 v76, v70
	v_rcp_f32_e32 v77, v66
	v_rcp_f32_e32 v79, v67
	v_fma_f32 v66, v76, v129, v189
	v_cmp_gt_f32_e32 vcc, s16, v66
	v_sub_f32_e32 v76, 1.0, v76
	v_mul_f32_e32 v76, v76, v129
	v_cndmask_b32_e64 v70, 0, 32, vcc
	v_ldexp_f32 v66, v66, v70
	v_log_f32_e32 v66, v66
	s_nop 0
	v_mul_f32_e32 v70, 0x3f317217, v66
	v_fma_f32 v70, v66, s17, -v70
	v_fmac_f32_e32 v70, 0x3377d1cf, v66
	v_fmac_f32_e32 v70, 0x3f317217, v66
	v_cmp_lt_f32_e64 s[0:1], |v66|, s86
	s_nop 1
	v_cndmask_b32_e64 v66, v66, v70, s[0:1]
	v_cndmask_b32_e32 v70, 0, v224, vcc
	v_sub_f32_e32 v66, v66, v70
	v_fma_f32 v70, v77, v199, v145
	v_cmp_gt_f32_e32 vcc, s16, v70
	v_sub_f32_e32 v77, 1.0, v77
	v_mul_f32_e32 v77, v77, v199
	v_cndmask_b32_e64 v78, 0, 32, vcc
	v_ldexp_f32 v70, v70, v78
	v_log_f32_e32 v70, v70
	s_nop 0
	v_mul_f32_e32 v78, 0x3f317217, v70
	v_fma_f32 v78, v70, s17, -v78
	v_fmac_f32_e32 v78, 0x3377d1cf, v70
	v_fmac_f32_e32 v78, 0x3f317217, v70
	v_cmp_lt_f32_e64 s[0:1], |v70|, s86
	s_nop 1
	v_cndmask_b32_e64 v70, v70, v78, s[0:1]
	v_cndmask_b32_e32 v78, 0, v224, vcc
	v_sub_f32_e32 v70, v70, v78
	v_rcp_f32_e32 v78, v71
	s_nop 0
	v_fma_f32 v67, v78, v127, v187
	v_cmp_gt_f32_e32 vcc, s16, v67
	v_sub_f32_e32 v78, 1.0, v78
	v_mul_f32_e32 v78, v78, v127
	v_cndmask_b32_e64 v71, 0, 32, vcc
	v_ldexp_f32 v67, v67, v71
	v_log_f32_e32 v67, v67
	s_nop 0
	v_mul_f32_e32 v71, 0x3f317217, v67
	v_fma_f32 v71, v67, s17, -v71
	v_fmac_f32_e32 v71, 0x3377d1cf, v67
	v_fmac_f32_e32 v71, 0x3f317217, v67
	v_cmp_lt_f32_e64 s[0:1], |v67|, s86
	s_nop 1
	v_cndmask_b32_e64 v67, v67, v71, s[0:1]
	v_cndmask_b32_e32 v71, 0, v224, vcc
	v_sub_f32_e32 v67, v67, v71
	v_fma_f32 v71, v79, v197, v141
	v_cmp_gt_f32_e32 vcc, s16, v71
	v_sub_f32_e32 v79, 1.0, v79
	v_mul_f32_e32 v79, v79, v197
	v_cndmask_b32_e64 v80, 0, 32, vcc
	v_ldexp_f32 v71, v71, v80
	v_log_f32_e32 v71, v71
	s_nop 0
	v_mul_f32_e32 v80, 0x3f317217, v71
	v_fma_f32 v80, v71, s17, -v80
	v_fmac_f32_e32 v80, 0x3377d1cf, v71
	v_fmac_f32_e32 v80, 0x3f317217, v71
	v_cmp_lt_f32_e64 s[0:1], |v71|, s86
	s_nop 1
	v_cndmask_b32_e64 v71, v71, v80, s[0:1]
	v_cndmask_b32_e32 v80, 0, v224, vcc
	v_sub_f32_e32 v71, v71, v80
	v_rcp_f32_e32 v80, v72
	s_nop 0
	v_fma_f32 v68, v80, v125, v143
	v_cmp_gt_f32_e32 vcc, s16, v68
	v_sub_f32_e32 v80, 1.0, v80
	v_mul_f32_e32 v80, v80, v125
	v_cndmask_b32_e64 v72, 0, 32, vcc
	v_ldexp_f32 v68, v68, v72
	v_log_f32_e32 v68, v68
	s_nop 0
	v_mul_f32_e32 v72, 0x3f317217, v68
	v_fma_f32 v72, v68, s17, -v72
	v_fmac_f32_e32 v72, 0x3377d1cf, v68
	v_fmac_f32_e32 v72, 0x3f317217, v68
	v_cmp_lt_f32_e64 s[0:1], |v68|, s86
	s_nop 1
	v_cndmask_b32_e64 v68, v68, v72, s[0:1]
	v_cndmask_b32_e32 v72, 0, v224, vcc
	v_sub_f32_e32 v68, v68, v72
	v_fma_f32 v72, v81, v195, v135
	v_cmp_gt_f32_e32 vcc, s16, v72
	v_sub_f32_e32 v81, 1.0, v81
	v_mul_f32_e32 v81, v81, v195
	v_cndmask_b32_e64 v82, 0, 32, vcc
	v_ldexp_f32 v72, v72, v82
	v_log_f32_e32 v72, v72
	s_nop 0
	v_mul_f32_e32 v82, 0x3f317217, v72
	v_fma_f32 v82, v72, s17, -v82
	v_fmac_f32_e32 v82, 0x3377d1cf, v72
	v_fmac_f32_e32 v82, 0x3f317217, v72
	v_cmp_lt_f32_e64 s[0:1], |v72|, s86
	s_nop 1
	v_cndmask_b32_e64 v72, v72, v82, s[0:1]
	v_cndmask_b32_e32 v82, 0, v224, vcc
	v_sub_f32_e32 v72, v72, v82
	v_rcp_f32_e32 v82, v73
	s_nop 0
	v_fma_f32 v69, v82, v123, v139
	v_cmp_gt_f32_e32 vcc, s16, v69
	v_sub_f32_e32 v82, 1.0, v82
	v_mul_f32_e32 v82, v82, v123
	v_cndmask_b32_e64 v73, 0, 32, vcc
	v_ldexp_f32 v69, v69, v73
	v_log_f32_e32 v69, v69
	s_nop 0
	v_mul_f32_e32 v73, 0x3f317217, v69
	v_fma_f32 v73, v69, s17, -v73
	v_fmac_f32_e32 v73, 0x3377d1cf, v69
	v_fmac_f32_e32 v73, 0x3f317217, v69
	v_cmp_lt_f32_e64 s[0:1], |v69|, s86
	s_nop 1
	v_cndmask_b32_e64 v69, v69, v73, s[0:1]
	v_cndmask_b32_e32 v73, 0, v224, vcc
	v_sub_f32_e32 v69, v69, v73
	v_fma_f32 v73, v83, v167, v131
	v_cmp_gt_f32_e32 vcc, s16, v73
	v_sub_f32_e32 v83, 1.0, v83
	v_mul_f32_e32 v83, v83, v167
	v_cndmask_b32_e64 v86, 0, 32, vcc
	v_ldexp_f32 v73, v73, v86
	v_log_f32_e32 v73, v73
	s_nop 0
	v_mul_f32_e32 v86, 0x3f317217, v73
	v_fma_f32 v86, v73, s17, -v86
	v_fmac_f32_e32 v86, 0x3377d1cf, v73
	v_fmac_f32_e32 v86, 0x3f317217, v73
	v_cmp_lt_f32_e64 s[0:1], |v73|, s86
	s_nop 1
	v_cndmask_b32_e64 v73, v73, v86, s[0:1]
	v_cndmask_b32_e32 v86, 0, v224, vcc
	v_sub_f32_e32 v73, v73, v86
	global_store_dwordx4 v[84:85], v[66:69], off offset:-3584 nt
	global_store_dwordx4 v[84:85], v[70:73], off offset:-3568 nt
	s_nop 0
	v_cvt_pk_bf16_f32 v66, v76, v78
	v_cvt_pk_bf16_f32 v67, v80, v82
	v_cvt_pk_bf16_f32 v68, v77, v79
	v_cvt_pk_bf16_f32 v69, v81, v83
	global_store_dwordx4 v[74:75], v[66:69], off offset:256 nt
	v_rcp_f32_e32 v70, v58
	v_rcp_f32_e32 v72, v59
	v_add_u32_e32 v66, 0x80, v164
	v_ashrrev_i32_e32 v67, 31, v66
	v_lshlrev_b64 v[68:69], 12, v[66:67]
	v_rcp_f32_e32 v67, v62
	v_rcp_f32_e32 v74, v60
	v_rcp_f32_e32 v76, v61
	v_lshl_add_u64 v[68:69], s[12:13], 0, v[68:69]
	v_fma_f32 v58, v67, v193, v171
	v_cmp_gt_f32_e32 vcc, s16, v58
	v_lshl_add_u64 v[68:69], v[68:69], 0, v[168:169]
	v_sub_f32_e32 v67, 1.0, v67
	v_cndmask_b32_e64 v62, 0, 32, vcc
	v_ldexp_f32 v58, v58, v62
	v_log_f32_e32 v58, v58
	v_mul_f32_e32 v67, v67, v193
	v_mul_f32_e32 v62, 0x3f317217, v58
	v_fma_f32 v62, v58, s17, -v62
	v_fmac_f32_e32 v62, 0x3377d1cf, v58
	v_fmac_f32_e32 v62, 0x3f317217, v58
	v_cmp_lt_f32_e64 s[0:1], |v58|, s86
	s_nop 1
	v_cndmask_b32_e64 v58, v58, v62, s[0:1]
	v_cndmask_b32_e32 v62, 0, v224, vcc
	v_sub_f32_e32 v58, v58, v62
	v_fma_f32 v62, v70, v207, v185
	v_cmp_gt_f32_e32 vcc, s16, v62
	v_sub_f32_e32 v70, 1.0, v70
	v_mul_f32_e32 v70, v70, v207
	v_cndmask_b32_e64 v71, 0, 32, vcc
	v_ldexp_f32 v62, v62, v71
	v_log_f32_e32 v62, v62
	s_nop 0
	v_mul_f32_e32 v71, 0x3f317217, v62
	v_fma_f32 v71, v62, s17, -v71
	v_fmac_f32_e32 v71, 0x3377d1cf, v62
	v_fmac_f32_e32 v71, 0x3f317217, v62
	v_cmp_lt_f32_e64 s[0:1], |v62|, s86
	s_nop 1
	v_cndmask_b32_e64 v62, v62, v71, s[0:1]
	v_cndmask_b32_e32 v71, 0, v224, vcc
	v_sub_f32_e32 v62, v62, v71
	v_rcp_f32_e32 v71, v63
	s_nop 0
	v_fma_f32 v59, v71, v191, v173
	v_cmp_gt_f32_e32 vcc, s16, v59
	v_sub_f32_e32 v71, 1.0, v71
	v_mul_f32_e32 v71, v71, v191
	v_cndmask_b32_e64 v63, 0, 32, vcc
	v_ldexp_f32 v59, v59, v63
	v_log_f32_e32 v59, v59
	s_nop 0
	v_mul_f32_e32 v63, 0x3f317217, v59
	v_fma_f32 v63, v59, s17, -v63
	v_fmac_f32_e32 v63, 0x3377d1cf, v59
	v_fmac_f32_e32 v63, 0x3f317217, v59
	v_cmp_lt_f32_e64 s[0:1], |v59|, s86
	s_nop 1
	v_cndmask_b32_e64 v59, v59, v63, s[0:1]
	v_cndmask_b32_e32 v63, 0, v224, vcc
	v_sub_f32_e32 v59, v59, v63
	v_fma_f32 v63, v72, v205, v183
	v_cmp_gt_f32_e32 vcc, s16, v63
	v_sub_f32_e32 v72, 1.0, v72
	v_mul_f32_e32 v72, v72, v205
	v_cndmask_b32_e64 v73, 0, 32, vcc
	v_ldexp_f32 v63, v63, v73
	v_log_f32_e32 v63, v63
	s_nop 0
	v_mul_f32_e32 v73, 0x3f317217, v63
	v_fma_f32 v73, v63, s17, -v73
	v_fmac_f32_e32 v73, 0x3377d1cf, v63
	v_fmac_f32_e32 v73, 0x3f317217, v63
	v_cmp_lt_f32_e64 s[0:1], |v63|, s86
	s_nop 1
	v_cndmask_b32_e64 v63, v63, v73, s[0:1]
	v_cndmask_b32_e32 v73, 0, v224, vcc
	v_sub_f32_e32 v63, v63, v73
	v_rcp_f32_e32 v73, v64
	s_nop 0
	v_fma_f32 v60, v73, v137, v175
	v_cmp_gt_f32_e32 vcc, s16, v60
	v_sub_f32_e32 v73, 1.0, v73
	v_mul_f32_e32 v73, v73, v137
	v_cndmask_b32_e64 v64, 0, 32, vcc
	v_ldexp_f32 v60, v60, v64
	v_log_f32_e32 v60, v60
	s_nop 0
	v_mul_f32_e32 v64, 0x3f317217, v60
	v_fma_f32 v64, v60, s17, -v64
	v_fmac_f32_e32 v64, 0x3377d1cf, v60
	v_fmac_f32_e32 v64, 0x3f317217, v60
	v_cmp_lt_f32_e64 s[0:1], |v60|, s86
	s_nop 1
	v_cndmask_b32_e64 v60, v60, v64, s[0:1]
	v_cndmask_b32_e32 v64, 0, v224, vcc
	v_sub_f32_e32 v60, v60, v64
	v_fma_f32 v64, v74, v203, v181
	v_cmp_gt_f32_e32 vcc, s16, v64
	v_sub_f32_e32 v74, 1.0, v74
	v_mul_f32_e32 v74, v74, v203
	v_cndmask_b32_e64 v75, 0, 32, vcc
	v_ldexp_f32 v64, v64, v75
	v_log_f32_e32 v64, v64
	s_nop 0
	v_mul_f32_e32 v75, 0x3f317217, v64
	v_fma_f32 v75, v64, s17, -v75
	v_fmac_f32_e32 v75, 0x3377d1cf, v64
	v_fmac_f32_e32 v75, 0x3f317217, v64
	v_cmp_lt_f32_e64 s[0:1], |v64|, s86
	s_nop 1
	v_cndmask_b32_e64 v64, v64, v75, s[0:1]
	v_cndmask_b32_e32 v75, 0, v224, vcc
	v_sub_f32_e32 v64, v64, v75
	v_rcp_f32_e32 v75, v65
	s_nop 0
	v_fma_f32 v61, v75, v133, v177
	v_cmp_gt_f32_e32 vcc, s16, v61
	v_sub_f32_e32 v75, 1.0, v75
	v_mul_f32_e32 v75, v75, v133
	v_cndmask_b32_e64 v65, 0, 32, vcc
	v_ldexp_f32 v61, v61, v65
	v_log_f32_e32 v61, v61
	s_nop 0
	v_mul_f32_e32 v65, 0x3f317217, v61
	v_fma_f32 v65, v61, s17, -v65
	v_fmac_f32_e32 v65, 0x3377d1cf, v61
	v_fmac_f32_e32 v65, 0x3f317217, v61
	v_cmp_lt_f32_e64 s[0:1], |v61|, s86
	s_nop 1
	v_cndmask_b32_e64 v61, v61, v65, s[0:1]
	v_cndmask_b32_e32 v65, 0, v224, vcc
	v_sub_f32_e32 v61, v61, v65
	v_fma_f32 v65, v76, v201, v179
	v_cmp_gt_f32_e32 vcc, s16, v65
	v_sub_f32_e32 v76, 1.0, v76
	v_mul_f32_e32 v76, v76, v201
	v_cndmask_b32_e64 v77, 0, 32, vcc
	v_ldexp_f32 v65, v65, v77
	v_log_f32_e32 v65, v65
	s_nop 0
	v_mul_f32_e32 v77, 0x3f317217, v65
	v_fma_f32 v77, v65, s17, -v77
	v_fmac_f32_e32 v77, 0x3377d1cf, v65
	v_fmac_f32_e32 v77, 0x3f317217, v65
	v_cmp_lt_f32_e64 s[0:1], |v65|, s86
	s_nop 1
	v_cndmask_b32_e64 v65, v65, v77, s[0:1]
	v_cndmask_b32_e32 v77, 0, v224, vcc
	v_sub_f32_e32 v65, v65, v77
	global_store_dwordx4 v[68:69], v[58:61], off offset:-4096 nt
	global_store_dwordx4 v[68:69], v[62:65], off offset:-4080 nt
	s_nop 0
	v_mad_i64_i32 v[58:59], s[0:1], v66, s8, v[208:209]
	v_cvt_pk_bf16_f32 v60, v67, v71
	v_lshl_add_u64 v[58:59], v[58:59], 0, v[210:211]
	v_cvt_pk_bf16_f32 v61, v73, v75
	v_cvt_pk_bf16_f32 v62, v70, v72
	v_cvt_pk_bf16_f32 v63, v74, v76
	global_store_dwordx4 v[58:59], v[60:63], off nt
	v_rcp_f32_e32 v65, v52
	v_rcp_f32_e32 v67, v53
	v_rcp_f32_e32 v60, v54
	v_rcp_f32_e32 v61, v50
	v_rcp_f32_e32 v63, v51
	v_fma_f32 v50, v60, v129, v189
	v_cmp_gt_f32_e32 vcc, s16, v50
	v_sub_f32_e32 v60, 1.0, v60
	v_mul_f32_e32 v60, v60, v129
	v_cndmask_b32_e64 v54, 0, 32, vcc
	v_ldexp_f32 v50, v50, v54
	v_log_f32_e32 v50, v50
	s_nop 0
	v_mul_f32_e32 v54, 0x3f317217, v50
	v_fma_f32 v54, v50, s17, -v54
	v_fmac_f32_e32 v54, 0x3377d1cf, v50
	v_fmac_f32_e32 v54, 0x3f317217, v50
	v_cmp_lt_f32_e64 s[0:1], |v50|, s86
	s_nop 1
	v_cndmask_b32_e64 v50, v50, v54, s[0:1]
	v_cndmask_b32_e32 v54, 0, v224, vcc
	v_sub_f32_e32 v50, v50, v54
	v_fma_f32 v54, v61, v199, v145
	v_cmp_gt_f32_e32 vcc, s16, v54
	v_sub_f32_e32 v61, 1.0, v61
	v_mul_f32_e32 v61, v61, v199
	v_cndmask_b32_e64 v62, 0, 32, vcc
	v_ldexp_f32 v54, v54, v62
	v_log_f32_e32 v54, v54
	s_nop 0
	v_mul_f32_e32 v62, 0x3f317217, v54
	v_fma_f32 v62, v54, s17, -v62
	v_fmac_f32_e32 v62, 0x3377d1cf, v54
	v_fmac_f32_e32 v62, 0x3f317217, v54
	v_cmp_lt_f32_e64 s[0:1], |v54|, s86
	s_nop 1
	v_cndmask_b32_e64 v54, v54, v62, s[0:1]
	v_cndmask_b32_e32 v62, 0, v224, vcc
	v_sub_f32_e32 v54, v54, v62
	v_rcp_f32_e32 v62, v55
	s_nop 0
	v_fma_f32 v51, v62, v127, v187
	v_cmp_gt_f32_e32 vcc, s16, v51
	v_sub_f32_e32 v62, 1.0, v62
	v_mul_f32_e32 v62, v62, v127
	v_cndmask_b32_e64 v55, 0, 32, vcc
	v_ldexp_f32 v51, v51, v55
	v_log_f32_e32 v51, v51
	s_nop 0
	v_mul_f32_e32 v55, 0x3f317217, v51
	v_fma_f32 v55, v51, s17, -v55
	v_fmac_f32_e32 v55, 0x3377d1cf, v51
	v_fmac_f32_e32 v55, 0x3f317217, v51
	v_cmp_lt_f32_e64 s[0:1], |v51|, s86
	s_nop 1
	v_cndmask_b32_e64 v51, v51, v55, s[0:1]
	v_cndmask_b32_e32 v55, 0, v224, vcc
	v_sub_f32_e32 v51, v51, v55
	v_fma_f32 v55, v63, v197, v141
	v_cmp_gt_f32_e32 vcc, s16, v55
	v_sub_f32_e32 v63, 1.0, v63
	v_mul_f32_e32 v63, v63, v197
	v_cndmask_b32_e64 v64, 0, 32, vcc
	v_ldexp_f32 v55, v55, v64
	v_log_f32_e32 v55, v55
	s_nop 0
	v_mul_f32_e32 v64, 0x3f317217, v55
	v_fma_f32 v64, v55, s17, -v64
	v_fmac_f32_e32 v64, 0x3377d1cf, v55
	v_fmac_f32_e32 v64, 0x3f317217, v55
	v_cmp_lt_f32_e64 s[0:1], |v55|, s86
	s_nop 1
	v_cndmask_b32_e64 v55, v55, v64, s[0:1]
	v_cndmask_b32_e32 v64, 0, v224, vcc
	v_sub_f32_e32 v55, v55, v64
	v_rcp_f32_e32 v64, v56
	s_nop 0
	v_fma_f32 v52, v64, v125, v143
	v_cmp_gt_f32_e32 vcc, s16, v52
	v_sub_f32_e32 v64, 1.0, v64
	v_mul_f32_e32 v64, v64, v125
	v_cndmask_b32_e64 v56, 0, 32, vcc
	v_ldexp_f32 v52, v52, v56
	v_log_f32_e32 v52, v52
	s_nop 0
	v_mul_f32_e32 v56, 0x3f317217, v52
	v_fma_f32 v56, v52, s17, -v56
	v_fmac_f32_e32 v56, 0x3377d1cf, v52
	v_fmac_f32_e32 v56, 0x3f317217, v52
	v_cmp_lt_f32_e64 s[0:1], |v52|, s86
	s_nop 1
	v_cndmask_b32_e64 v52, v52, v56, s[0:1]
	v_cndmask_b32_e32 v56, 0, v224, vcc
	v_sub_f32_e32 v52, v52, v56
	v_fma_f32 v56, v65, v195, v135
	v_cmp_gt_f32_e32 vcc, s16, v56
	v_sub_f32_e32 v65, 1.0, v65
	v_mul_f32_e32 v65, v65, v195
	v_cndmask_b32_e64 v66, 0, 32, vcc
	v_ldexp_f32 v56, v56, v66
	v_log_f32_e32 v56, v56
	s_nop 0
	v_mul_f32_e32 v66, 0x3f317217, v56
	v_fma_f32 v66, v56, s17, -v66
	v_fmac_f32_e32 v66, 0x3377d1cf, v56
	v_fmac_f32_e32 v66, 0x3f317217, v56
	v_cmp_lt_f32_e64 s[0:1], |v56|, s86
	s_nop 1
	v_cndmask_b32_e64 v56, v56, v66, s[0:1]
	v_cndmask_b32_e32 v66, 0, v224, vcc
	v_sub_f32_e32 v56, v56, v66
	v_rcp_f32_e32 v66, v57
	s_nop 0
	v_fma_f32 v53, v66, v123, v139
	v_cmp_gt_f32_e32 vcc, s16, v53
	v_sub_f32_e32 v66, 1.0, v66
	v_mul_f32_e32 v66, v66, v123
	v_cndmask_b32_e64 v57, 0, 32, vcc
	v_ldexp_f32 v53, v53, v57
	v_log_f32_e32 v53, v53
	s_nop 0
	v_mul_f32_e32 v57, 0x3f317217, v53
	v_fma_f32 v57, v53, s17, -v57
	v_fmac_f32_e32 v57, 0x3377d1cf, v53
	v_fmac_f32_e32 v57, 0x3f317217, v53
	v_cmp_lt_f32_e64 s[0:1], |v53|, s86
	s_nop 1
	v_cndmask_b32_e64 v53, v53, v57, s[0:1]
	v_cndmask_b32_e32 v57, 0, v224, vcc
	v_sub_f32_e32 v53, v53, v57
	v_fma_f32 v57, v67, v167, v131
	v_cmp_gt_f32_e32 vcc, s16, v57
	v_sub_f32_e32 v67, 1.0, v67
	v_mul_f32_e32 v67, v67, v167
	v_cndmask_b32_e64 v70, 0, 32, vcc
	v_ldexp_f32 v57, v57, v70
	v_log_f32_e32 v57, v57
	s_nop 0
	v_mul_f32_e32 v70, 0x3f317217, v57
	v_fma_f32 v70, v57, s17, -v70
	v_fmac_f32_e32 v70, 0x3377d1cf, v57
	v_fmac_f32_e32 v70, 0x3f317217, v57
	v_cmp_lt_f32_e64 s[0:1], |v57|, s86
	s_nop 1
	v_cndmask_b32_e64 v57, v57, v70, s[0:1]
	v_cndmask_b32_e32 v70, 0, v224, vcc
	v_sub_f32_e32 v57, v57, v70
	global_store_dwordx4 v[68:69], v[50:53], off offset:-3584 nt
	global_store_dwordx4 v[68:69], v[54:57], off offset:-3568 nt
	s_nop 0
	v_cvt_pk_bf16_f32 v50, v60, v62
	v_cvt_pk_bf16_f32 v51, v64, v66
	v_cvt_pk_bf16_f32 v52, v61, v63
	v_cvt_pk_bf16_f32 v53, v65, v67
	global_store_dwordx4 v[58:59], v[50:53], off offset:256 nt
	v_rcp_f32_e32 v54, v42
	v_rcp_f32_e32 v56, v43
	v_add_u32_e32 v50, 0x90, v164
	v_ashrrev_i32_e32 v51, 31, v50
	v_lshlrev_b64 v[52:53], 12, v[50:51]
	v_rcp_f32_e32 v51, v46
	v_rcp_f32_e32 v58, v44
	v_rcp_f32_e32 v60, v45
	v_lshl_add_u64 v[52:53], s[12:13], 0, v[52:53]
	v_fma_f32 v42, v51, v193, v171
	v_cmp_gt_f32_e32 vcc, s16, v42
	v_lshl_add_u64 v[52:53], v[52:53], 0, v[168:169]
	v_sub_f32_e32 v51, 1.0, v51
	v_cndmask_b32_e64 v46, 0, 32, vcc
	v_ldexp_f32 v42, v42, v46
	v_log_f32_e32 v42, v42
	v_mul_f32_e32 v51, v51, v193
	v_mul_f32_e32 v46, 0x3f317217, v42
	v_fma_f32 v46, v42, s17, -v46
	v_fmac_f32_e32 v46, 0x3377d1cf, v42
	v_fmac_f32_e32 v46, 0x3f317217, v42
	v_cmp_lt_f32_e64 s[0:1], |v42|, s86
	s_nop 1
	v_cndmask_b32_e64 v42, v42, v46, s[0:1]
	v_cndmask_b32_e32 v46, 0, v224, vcc
	v_sub_f32_e32 v42, v42, v46
	v_fma_f32 v46, v54, v207, v185
	v_cmp_gt_f32_e32 vcc, s16, v46
	v_sub_f32_e32 v54, 1.0, v54
	v_mul_f32_e32 v54, v54, v207
	v_cndmask_b32_e64 v55, 0, 32, vcc
	v_ldexp_f32 v46, v46, v55
	v_log_f32_e32 v46, v46
	s_nop 0
	v_mul_f32_e32 v55, 0x3f317217, v46
	v_fma_f32 v55, v46, s17, -v55
	v_fmac_f32_e32 v55, 0x3377d1cf, v46
	v_fmac_f32_e32 v55, 0x3f317217, v46
	v_cmp_lt_f32_e64 s[0:1], |v46|, s86
	s_nop 1
	v_cndmask_b32_e64 v46, v46, v55, s[0:1]
	v_cndmask_b32_e32 v55, 0, v224, vcc
	v_sub_f32_e32 v46, v46, v55
	v_rcp_f32_e32 v55, v47
	s_nop 0
	v_fma_f32 v43, v55, v191, v173
	v_cmp_gt_f32_e32 vcc, s16, v43
	v_sub_f32_e32 v55, 1.0, v55
	v_mul_f32_e32 v55, v55, v191
	v_cndmask_b32_e64 v47, 0, 32, vcc
	v_ldexp_f32 v43, v43, v47
	v_log_f32_e32 v43, v43
	s_nop 0
	v_mul_f32_e32 v47, 0x3f317217, v43
	v_fma_f32 v47, v43, s17, -v47
	v_fmac_f32_e32 v47, 0x3377d1cf, v43
	v_fmac_f32_e32 v47, 0x3f317217, v43
	v_cmp_lt_f32_e64 s[0:1], |v43|, s86
	s_nop 1
	v_cndmask_b32_e64 v43, v43, v47, s[0:1]
	v_cndmask_b32_e32 v47, 0, v224, vcc
	v_sub_f32_e32 v43, v43, v47
	v_fma_f32 v47, v56, v205, v183
	v_cmp_gt_f32_e32 vcc, s16, v47
	v_sub_f32_e32 v56, 1.0, v56
	v_mul_f32_e32 v56, v56, v205
	v_cndmask_b32_e64 v57, 0, 32, vcc
	v_ldexp_f32 v47, v47, v57
	v_log_f32_e32 v47, v47
	s_nop 0
	v_mul_f32_e32 v57, 0x3f317217, v47
	v_fma_f32 v57, v47, s17, -v57
	v_fmac_f32_e32 v57, 0x3377d1cf, v47
	v_fmac_f32_e32 v57, 0x3f317217, v47
	v_cmp_lt_f32_e64 s[0:1], |v47|, s86
	s_nop 1
	v_cndmask_b32_e64 v47, v47, v57, s[0:1]
	v_cndmask_b32_e32 v57, 0, v224, vcc
	v_sub_f32_e32 v47, v47, v57
	v_rcp_f32_e32 v57, v48
	s_nop 0
	v_fma_f32 v44, v57, v137, v175
	v_cmp_gt_f32_e32 vcc, s16, v44
	v_sub_f32_e32 v57, 1.0, v57
	v_mul_f32_e32 v57, v57, v137
	v_cndmask_b32_e64 v48, 0, 32, vcc
	v_ldexp_f32 v44, v44, v48
	v_log_f32_e32 v44, v44
	s_nop 0
	v_mul_f32_e32 v48, 0x3f317217, v44
	v_fma_f32 v48, v44, s17, -v48
	v_fmac_f32_e32 v48, 0x3377d1cf, v44
	v_fmac_f32_e32 v48, 0x3f317217, v44
	v_cmp_lt_f32_e64 s[0:1], |v44|, s86
	s_nop 1
	v_cndmask_b32_e64 v44, v44, v48, s[0:1]
	v_cndmask_b32_e32 v48, 0, v224, vcc
	v_sub_f32_e32 v44, v44, v48
	v_fma_f32 v48, v58, v203, v181
	v_cmp_gt_f32_e32 vcc, s16, v48
	v_sub_f32_e32 v58, 1.0, v58
	v_mul_f32_e32 v58, v58, v203
	v_cndmask_b32_e64 v59, 0, 32, vcc
	v_ldexp_f32 v48, v48, v59
	v_log_f32_e32 v48, v48
	s_nop 0
	v_mul_f32_e32 v59, 0x3f317217, v48
	v_fma_f32 v59, v48, s17, -v59
	v_fmac_f32_e32 v59, 0x3377d1cf, v48
	v_fmac_f32_e32 v59, 0x3f317217, v48
	v_cmp_lt_f32_e64 s[0:1], |v48|, s86
	s_nop 1
	v_cndmask_b32_e64 v48, v48, v59, s[0:1]
	v_cndmask_b32_e32 v59, 0, v224, vcc
	v_sub_f32_e32 v48, v48, v59
	v_rcp_f32_e32 v59, v49
	s_nop 0
	v_fma_f32 v45, v59, v133, v177
	v_cmp_gt_f32_e32 vcc, s16, v45
	v_sub_f32_e32 v59, 1.0, v59
	v_mul_f32_e32 v59, v59, v133
	v_cndmask_b32_e64 v49, 0, 32, vcc
	v_ldexp_f32 v45, v45, v49
	v_log_f32_e32 v45, v45
	s_nop 0
	v_mul_f32_e32 v49, 0x3f317217, v45
	v_fma_f32 v49, v45, s17, -v49
	v_fmac_f32_e32 v49, 0x3377d1cf, v45
	v_fmac_f32_e32 v49, 0x3f317217, v45
	v_cmp_lt_f32_e64 s[0:1], |v45|, s86
	s_nop 1
	v_cndmask_b32_e64 v45, v45, v49, s[0:1]
	v_cndmask_b32_e32 v49, 0, v224, vcc
	v_sub_f32_e32 v45, v45, v49
	v_fma_f32 v49, v60, v201, v179
	v_cmp_gt_f32_e32 vcc, s16, v49
	v_sub_f32_e32 v60, 1.0, v60
	v_mul_f32_e32 v60, v60, v201
	v_cndmask_b32_e64 v61, 0, 32, vcc
	v_ldexp_f32 v49, v49, v61
	v_log_f32_e32 v49, v49
	s_nop 0
	v_mul_f32_e32 v61, 0x3f317217, v49
	v_fma_f32 v61, v49, s17, -v61
	v_fmac_f32_e32 v61, 0x3377d1cf, v49
	v_fmac_f32_e32 v61, 0x3f317217, v49
	v_cmp_lt_f32_e64 s[0:1], |v49|, s86
	s_nop 1
	v_cndmask_b32_e64 v49, v49, v61, s[0:1]
	v_cndmask_b32_e32 v61, 0, v224, vcc
	v_sub_f32_e32 v49, v49, v61
	global_store_dwordx4 v[52:53], v[42:45], off offset:-4096 nt
	global_store_dwordx4 v[52:53], v[46:49], off offset:-4080 nt
	s_nop 0
	v_mad_i64_i32 v[42:43], s[0:1], v50, s8, v[208:209]
	v_cvt_pk_bf16_f32 v44, v51, v55
	v_lshl_add_u64 v[42:43], v[42:43], 0, v[210:211]
	v_cvt_pk_bf16_f32 v45, v57, v59
	v_cvt_pk_bf16_f32 v46, v54, v56
	v_cvt_pk_bf16_f32 v47, v58, v60
	global_store_dwordx4 v[42:43], v[44:47], off nt
	v_rcp_f32_e32 v49, v36
	v_rcp_f32_e32 v51, v37
	v_rcp_f32_e32 v44, v38
	v_rcp_f32_e32 v45, v34
	v_rcp_f32_e32 v47, v35
	v_fma_f32 v34, v44, v129, v189
	v_cmp_gt_f32_e32 vcc, s16, v34
	v_sub_f32_e32 v44, 1.0, v44
	v_mul_f32_e32 v44, v44, v129
	v_cndmask_b32_e64 v38, 0, 32, vcc
	v_ldexp_f32 v34, v34, v38
	v_log_f32_e32 v34, v34
	s_nop 0
	v_mul_f32_e32 v38, 0x3f317217, v34
	v_fma_f32 v38, v34, s17, -v38
	v_fmac_f32_e32 v38, 0x3377d1cf, v34
	v_fmac_f32_e32 v38, 0x3f317217, v34
	v_cmp_lt_f32_e64 s[0:1], |v34|, s86
	s_nop 1
	v_cndmask_b32_e64 v34, v34, v38, s[0:1]
	v_cndmask_b32_e32 v38, 0, v224, vcc
	v_sub_f32_e32 v34, v34, v38
	v_fma_f32 v38, v45, v199, v145
	v_cmp_gt_f32_e32 vcc, s16, v38
	v_sub_f32_e32 v45, 1.0, v45
	v_mul_f32_e32 v45, v45, v199
	v_cndmask_b32_e64 v46, 0, 32, vcc
	v_ldexp_f32 v38, v38, v46
	v_log_f32_e32 v38, v38
	s_nop 0
	v_mul_f32_e32 v46, 0x3f317217, v38
	v_fma_f32 v46, v38, s17, -v46
	v_fmac_f32_e32 v46, 0x3377d1cf, v38
	v_fmac_f32_e32 v46, 0x3f317217, v38
	v_cmp_lt_f32_e64 s[0:1], |v38|, s86
	s_nop 1
	v_cndmask_b32_e64 v38, v38, v46, s[0:1]
	v_cndmask_b32_e32 v46, 0, v224, vcc
	v_sub_f32_e32 v38, v38, v46
	v_rcp_f32_e32 v46, v39
	s_nop 0
	v_fma_f32 v35, v46, v127, v187
	v_cmp_gt_f32_e32 vcc, s16, v35
	v_sub_f32_e32 v46, 1.0, v46
	v_mul_f32_e32 v46, v46, v127
	v_cndmask_b32_e64 v39, 0, 32, vcc
	v_ldexp_f32 v35, v35, v39
	v_log_f32_e32 v35, v35
	s_nop 0
	v_mul_f32_e32 v39, 0x3f317217, v35
	v_fma_f32 v39, v35, s17, -v39
	v_fmac_f32_e32 v39, 0x3377d1cf, v35
	v_fmac_f32_e32 v39, 0x3f317217, v35
	v_cmp_lt_f32_e64 s[0:1], |v35|, s86
	s_nop 1
	v_cndmask_b32_e64 v35, v35, v39, s[0:1]
	v_cndmask_b32_e32 v39, 0, v224, vcc
	v_sub_f32_e32 v35, v35, v39
	v_fma_f32 v39, v47, v197, v141
	v_cmp_gt_f32_e32 vcc, s16, v39
	v_sub_f32_e32 v47, 1.0, v47
	v_mul_f32_e32 v47, v47, v197
	v_cndmask_b32_e64 v48, 0, 32, vcc
	v_ldexp_f32 v39, v39, v48
	v_log_f32_e32 v39, v39
	s_nop 0
	v_mul_f32_e32 v48, 0x3f317217, v39
	v_fma_f32 v48, v39, s17, -v48
	v_fmac_f32_e32 v48, 0x3377d1cf, v39
	v_fmac_f32_e32 v48, 0x3f317217, v39
	v_cmp_lt_f32_e64 s[0:1], |v39|, s86
	s_nop 1
	v_cndmask_b32_e64 v39, v39, v48, s[0:1]
	v_cndmask_b32_e32 v48, 0, v224, vcc
	v_sub_f32_e32 v39, v39, v48
	v_rcp_f32_e32 v48, v40
	s_nop 0
	v_fma_f32 v36, v48, v125, v143
	v_cmp_gt_f32_e32 vcc, s16, v36
	v_sub_f32_e32 v48, 1.0, v48
	v_mul_f32_e32 v48, v48, v125
	v_cndmask_b32_e64 v40, 0, 32, vcc
	v_ldexp_f32 v36, v36, v40
	v_log_f32_e32 v36, v36
	s_nop 0
	v_mul_f32_e32 v40, 0x3f317217, v36
	v_fma_f32 v40, v36, s17, -v40
	v_fmac_f32_e32 v40, 0x3377d1cf, v36
	v_fmac_f32_e32 v40, 0x3f317217, v36
	v_cmp_lt_f32_e64 s[0:1], |v36|, s86
	s_nop 1
	v_cndmask_b32_e64 v36, v36, v40, s[0:1]
	v_cndmask_b32_e32 v40, 0, v224, vcc
	v_sub_f32_e32 v36, v36, v40
	v_fma_f32 v40, v49, v195, v135
	v_cmp_gt_f32_e32 vcc, s16, v40
	v_sub_f32_e32 v49, 1.0, v49
	v_mul_f32_e32 v49, v49, v195
	v_cndmask_b32_e64 v50, 0, 32, vcc
	v_ldexp_f32 v40, v40, v50
	v_log_f32_e32 v40, v40
	s_nop 0
	v_mul_f32_e32 v50, 0x3f317217, v40
	v_fma_f32 v50, v40, s17, -v50
	v_fmac_f32_e32 v50, 0x3377d1cf, v40
	v_fmac_f32_e32 v50, 0x3f317217, v40
	v_cmp_lt_f32_e64 s[0:1], |v40|, s86
	s_nop 1
	v_cndmask_b32_e64 v40, v40, v50, s[0:1]
	v_cndmask_b32_e32 v50, 0, v224, vcc
	v_sub_f32_e32 v40, v40, v50
	v_rcp_f32_e32 v50, v41
	s_nop 0
	v_fma_f32 v37, v50, v123, v139
	v_cmp_gt_f32_e32 vcc, s16, v37
	v_sub_f32_e32 v50, 1.0, v50
	v_mul_f32_e32 v50, v50, v123
	v_cndmask_b32_e64 v41, 0, 32, vcc
	v_ldexp_f32 v37, v37, v41
	v_log_f32_e32 v37, v37
	s_nop 0
	v_mul_f32_e32 v41, 0x3f317217, v37
	v_fma_f32 v41, v37, s17, -v41
	v_fmac_f32_e32 v41, 0x3377d1cf, v37
	v_fmac_f32_e32 v41, 0x3f317217, v37
	v_cmp_lt_f32_e64 s[0:1], |v37|, s86
	s_nop 1
	v_cndmask_b32_e64 v37, v37, v41, s[0:1]
	v_cndmask_b32_e32 v41, 0, v224, vcc
	v_sub_f32_e32 v37, v37, v41
	v_fma_f32 v41, v51, v167, v131
	v_cmp_gt_f32_e32 vcc, s16, v41
	v_sub_f32_e32 v51, 1.0, v51
	v_mul_f32_e32 v51, v51, v167
	v_cndmask_b32_e64 v54, 0, 32, vcc
	v_ldexp_f32 v41, v41, v54
	v_log_f32_e32 v41, v41
	s_nop 0
	v_mul_f32_e32 v54, 0x3f317217, v41
	v_fma_f32 v54, v41, s17, -v54
	v_fmac_f32_e32 v54, 0x3377d1cf, v41
	v_fmac_f32_e32 v54, 0x3f317217, v41
	v_cmp_lt_f32_e64 s[0:1], |v41|, s86
	s_nop 1
	v_cndmask_b32_e64 v41, v41, v54, s[0:1]
	v_cndmask_b32_e32 v54, 0, v224, vcc
	v_sub_f32_e32 v41, v41, v54
	global_store_dwordx4 v[52:53], v[34:37], off offset:-3584 nt
	global_store_dwordx4 v[52:53], v[38:41], off offset:-3568 nt
	s_nop 0
	v_cvt_pk_bf16_f32 v34, v44, v46
	v_cvt_pk_bf16_f32 v35, v48, v50
	v_cvt_pk_bf16_f32 v36, v45, v47
	v_cvt_pk_bf16_f32 v37, v49, v51
	global_store_dwordx4 v[42:43], v[34:37], off offset:256 nt
	v_rcp_f32_e32 v38, v26
	v_rcp_f32_e32 v40, v27
	v_add_u32_e32 v34, 0xa0, v164
	v_ashrrev_i32_e32 v35, 31, v34
	v_lshlrev_b64 v[36:37], 12, v[34:35]
	v_rcp_f32_e32 v35, v30
	v_rcp_f32_e32 v42, v28
	v_rcp_f32_e32 v44, v29
	v_lshl_add_u64 v[36:37], s[12:13], 0, v[36:37]
	v_fma_f32 v26, v35, v193, v171
	v_cmp_gt_f32_e32 vcc, s16, v26
	v_lshl_add_u64 v[36:37], v[36:37], 0, v[168:169]
	v_sub_f32_e32 v35, 1.0, v35
	v_cndmask_b32_e64 v30, 0, 32, vcc
	v_ldexp_f32 v26, v26, v30
	v_log_f32_e32 v26, v26
	v_mul_f32_e32 v35, v35, v193
	v_mul_f32_e32 v30, 0x3f317217, v26
	v_fma_f32 v30, v26, s17, -v30
	v_fmac_f32_e32 v30, 0x3377d1cf, v26
	v_fmac_f32_e32 v30, 0x3f317217, v26
	v_cmp_lt_f32_e64 s[0:1], |v26|, s86
	s_nop 1
	v_cndmask_b32_e64 v26, v26, v30, s[0:1]
	v_cndmask_b32_e32 v30, 0, v224, vcc
	v_sub_f32_e32 v26, v26, v30
	v_fma_f32 v30, v38, v207, v185
	v_cmp_gt_f32_e32 vcc, s16, v30
	v_sub_f32_e32 v38, 1.0, v38
	v_mul_f32_e32 v38, v38, v207
	v_cndmask_b32_e64 v39, 0, 32, vcc
	v_ldexp_f32 v30, v30, v39
	v_log_f32_e32 v30, v30
	s_nop 0
	v_mul_f32_e32 v39, 0x3f317217, v30
	v_fma_f32 v39, v30, s17, -v39
	v_fmac_f32_e32 v39, 0x3377d1cf, v30
	v_fmac_f32_e32 v39, 0x3f317217, v30
	v_cmp_lt_f32_e64 s[0:1], |v30|, s86
	s_nop 1
	v_cndmask_b32_e64 v30, v30, v39, s[0:1]
	v_cndmask_b32_e32 v39, 0, v224, vcc
	v_sub_f32_e32 v30, v30, v39
	v_rcp_f32_e32 v39, v31
	s_nop 0
	v_fma_f32 v27, v39, v191, v173
	v_cmp_gt_f32_e32 vcc, s16, v27
	v_sub_f32_e32 v39, 1.0, v39
	v_mul_f32_e32 v39, v39, v191
	v_cndmask_b32_e64 v31, 0, 32, vcc
	v_ldexp_f32 v27, v27, v31
	v_log_f32_e32 v27, v27
	s_nop 0
	v_mul_f32_e32 v31, 0x3f317217, v27
	v_fma_f32 v31, v27, s17, -v31
	v_fmac_f32_e32 v31, 0x3377d1cf, v27
	v_fmac_f32_e32 v31, 0x3f317217, v27
	v_cmp_lt_f32_e64 s[0:1], |v27|, s86
	s_nop 1
	v_cndmask_b32_e64 v27, v27, v31, s[0:1]
	v_cndmask_b32_e32 v31, 0, v224, vcc
	v_sub_f32_e32 v27, v27, v31
	v_fma_f32 v31, v40, v205, v183
	v_cmp_gt_f32_e32 vcc, s16, v31
	v_sub_f32_e32 v40, 1.0, v40
	v_mul_f32_e32 v40, v40, v205
	v_cndmask_b32_e64 v41, 0, 32, vcc
	v_ldexp_f32 v31, v31, v41
	v_log_f32_e32 v31, v31
	s_nop 0
	v_mul_f32_e32 v41, 0x3f317217, v31
	v_fma_f32 v41, v31, s17, -v41
	v_fmac_f32_e32 v41, 0x3377d1cf, v31
	v_fmac_f32_e32 v41, 0x3f317217, v31
	v_cmp_lt_f32_e64 s[0:1], |v31|, s86
	s_nop 1
	v_cndmask_b32_e64 v31, v31, v41, s[0:1]
	v_cndmask_b32_e32 v41, 0, v224, vcc
	v_sub_f32_e32 v31, v31, v41
	v_rcp_f32_e32 v41, v32
	s_nop 0
	v_fma_f32 v28, v41, v137, v175
	v_cmp_gt_f32_e32 vcc, s16, v28
	v_sub_f32_e32 v41, 1.0, v41
	v_mul_f32_e32 v41, v41, v137
	v_cndmask_b32_e64 v32, 0, 32, vcc
	v_ldexp_f32 v28, v28, v32
	v_log_f32_e32 v28, v28
	s_nop 0
	v_mul_f32_e32 v32, 0x3f317217, v28
	v_fma_f32 v32, v28, s17, -v32
	v_fmac_f32_e32 v32, 0x3377d1cf, v28
	v_fmac_f32_e32 v32, 0x3f317217, v28
	v_cmp_lt_f32_e64 s[0:1], |v28|, s86
	s_nop 1
	v_cndmask_b32_e64 v28, v28, v32, s[0:1]
	v_cndmask_b32_e32 v32, 0, v224, vcc
	v_sub_f32_e32 v28, v28, v32
	v_fma_f32 v32, v42, v203, v181
	v_cmp_gt_f32_e32 vcc, s16, v32
	v_sub_f32_e32 v42, 1.0, v42
	v_mul_f32_e32 v42, v42, v203
	v_cndmask_b32_e64 v43, 0, 32, vcc
	v_ldexp_f32 v32, v32, v43
	v_log_f32_e32 v32, v32
	s_nop 0
	v_mul_f32_e32 v43, 0x3f317217, v32
	v_fma_f32 v43, v32, s17, -v43
	v_fmac_f32_e32 v43, 0x3377d1cf, v32
	v_fmac_f32_e32 v43, 0x3f317217, v32
	v_cmp_lt_f32_e64 s[0:1], |v32|, s86
	s_nop 1
	v_cndmask_b32_e64 v32, v32, v43, s[0:1]
	v_cndmask_b32_e32 v43, 0, v224, vcc
	v_sub_f32_e32 v32, v32, v43
	v_rcp_f32_e32 v43, v33
	s_nop 0
	v_fma_f32 v29, v43, v133, v177
	v_cmp_gt_f32_e32 vcc, s16, v29
	v_sub_f32_e32 v43, 1.0, v43
	v_mul_f32_e32 v43, v43, v133
	v_cndmask_b32_e64 v33, 0, 32, vcc
	v_ldexp_f32 v29, v29, v33
	v_log_f32_e32 v29, v29
	s_nop 0
	v_mul_f32_e32 v33, 0x3f317217, v29
	v_fma_f32 v33, v29, s17, -v33
	v_fmac_f32_e32 v33, 0x3377d1cf, v29
	v_fmac_f32_e32 v33, 0x3f317217, v29
	v_cmp_lt_f32_e64 s[0:1], |v29|, s86
	s_nop 1
	v_cndmask_b32_e64 v29, v29, v33, s[0:1]
	v_cndmask_b32_e32 v33, 0, v224, vcc
	v_sub_f32_e32 v29, v29, v33
	v_fma_f32 v33, v44, v201, v179
	v_cmp_gt_f32_e32 vcc, s16, v33
	v_sub_f32_e32 v44, 1.0, v44
	v_mul_f32_e32 v44, v44, v201
	v_cndmask_b32_e64 v45, 0, 32, vcc
	v_ldexp_f32 v33, v33, v45
	v_log_f32_e32 v33, v33
	s_nop 0
	v_mul_f32_e32 v45, 0x3f317217, v33
	v_fma_f32 v45, v33, s17, -v45
	v_fmac_f32_e32 v45, 0x3377d1cf, v33
	v_fmac_f32_e32 v45, 0x3f317217, v33
	v_cmp_lt_f32_e64 s[0:1], |v33|, s86
	s_nop 1
	v_cndmask_b32_e64 v33, v33, v45, s[0:1]
	v_cndmask_b32_e32 v45, 0, v224, vcc
	v_sub_f32_e32 v33, v33, v45
	global_store_dwordx4 v[36:37], v[26:29], off offset:-4096 nt
	global_store_dwordx4 v[36:37], v[30:33], off offset:-4080 nt
	s_nop 0
	v_mad_i64_i32 v[26:27], s[0:1], v34, s8, v[208:209]
	v_cvt_pk_bf16_f32 v28, v35, v39
	v_lshl_add_u64 v[26:27], v[26:27], 0, v[210:211]
	v_cvt_pk_bf16_f32 v29, v41, v43
	v_cvt_pk_bf16_f32 v30, v38, v40
	v_cvt_pk_bf16_f32 v31, v42, v44
	global_store_dwordx4 v[26:27], v[28:31], off nt
	v_rcp_f32_e32 v33, v20
	v_rcp_f32_e32 v35, v21
	v_rcp_f32_e32 v28, v22
	v_rcp_f32_e32 v29, v18
	v_rcp_f32_e32 v31, v19
	v_fma_f32 v18, v28, v129, v189
	v_cmp_gt_f32_e32 vcc, s16, v18
	v_sub_f32_e32 v28, 1.0, v28
	v_mul_f32_e32 v28, v28, v129
	v_cndmask_b32_e64 v22, 0, 32, vcc
	v_ldexp_f32 v18, v18, v22
	v_log_f32_e32 v18, v18
	s_nop 0
	v_mul_f32_e32 v22, 0x3f317217, v18
	v_fma_f32 v22, v18, s17, -v22
	v_fmac_f32_e32 v22, 0x3377d1cf, v18
	v_fmac_f32_e32 v22, 0x3f317217, v18
	v_cmp_lt_f32_e64 s[0:1], |v18|, s86
	s_nop 1
	v_cndmask_b32_e64 v18, v18, v22, s[0:1]
	v_cndmask_b32_e32 v22, 0, v224, vcc
	v_sub_f32_e32 v18, v18, v22
	v_fma_f32 v22, v29, v199, v145
	v_cmp_gt_f32_e32 vcc, s16, v22
	v_sub_f32_e32 v29, 1.0, v29
	v_mul_f32_e32 v29, v29, v199
	v_cndmask_b32_e64 v30, 0, 32, vcc
	v_ldexp_f32 v22, v22, v30
	v_log_f32_e32 v22, v22
	s_nop 0
	v_mul_f32_e32 v30, 0x3f317217, v22
	v_fma_f32 v30, v22, s17, -v30
	v_fmac_f32_e32 v30, 0x3377d1cf, v22
	v_fmac_f32_e32 v30, 0x3f317217, v22
	v_cmp_lt_f32_e64 s[0:1], |v22|, s86
	s_nop 1
	v_cndmask_b32_e64 v22, v22, v30, s[0:1]
	v_cndmask_b32_e32 v30, 0, v224, vcc
	v_sub_f32_e32 v22, v22, v30
	v_rcp_f32_e32 v30, v23
	s_nop 0
	v_fma_f32 v19, v30, v127, v187
	v_cmp_gt_f32_e32 vcc, s16, v19
	v_sub_f32_e32 v30, 1.0, v30
	v_mul_f32_e32 v30, v30, v127
	v_cndmask_b32_e64 v23, 0, 32, vcc
	v_ldexp_f32 v19, v19, v23
	v_log_f32_e32 v19, v19
	s_nop 0
	v_mul_f32_e32 v23, 0x3f317217, v19
	v_fma_f32 v23, v19, s17, -v23
	v_fmac_f32_e32 v23, 0x3377d1cf, v19
	v_fmac_f32_e32 v23, 0x3f317217, v19
	v_cmp_lt_f32_e64 s[0:1], |v19|, s86
	s_nop 1
	v_cndmask_b32_e64 v19, v19, v23, s[0:1]
	v_cndmask_b32_e32 v23, 0, v224, vcc
	v_sub_f32_e32 v19, v19, v23
	v_fma_f32 v23, v31, v197, v141
	v_cmp_gt_f32_e32 vcc, s16, v23
	v_sub_f32_e32 v31, 1.0, v31
	v_mul_f32_e32 v31, v31, v197
	v_cndmask_b32_e64 v32, 0, 32, vcc
	v_ldexp_f32 v23, v23, v32
	v_log_f32_e32 v23, v23
	s_nop 0
	v_mul_f32_e32 v32, 0x3f317217, v23
	v_fma_f32 v32, v23, s17, -v32
	v_fmac_f32_e32 v32, 0x3377d1cf, v23
	v_fmac_f32_e32 v32, 0x3f317217, v23
	v_cmp_lt_f32_e64 s[0:1], |v23|, s86
	s_nop 1
	v_cndmask_b32_e64 v23, v23, v32, s[0:1]
	v_cndmask_b32_e32 v32, 0, v224, vcc
	v_sub_f32_e32 v23, v23, v32
	v_rcp_f32_e32 v32, v24
	s_nop 0
	v_fma_f32 v20, v32, v125, v143
	v_cmp_gt_f32_e32 vcc, s16, v20
	v_sub_f32_e32 v32, 1.0, v32
	v_mul_f32_e32 v32, v32, v125
	v_cndmask_b32_e64 v24, 0, 32, vcc
	v_ldexp_f32 v20, v20, v24
	v_log_f32_e32 v20, v20
	s_nop 0
	v_mul_f32_e32 v24, 0x3f317217, v20
	v_fma_f32 v24, v20, s17, -v24
	v_fmac_f32_e32 v24, 0x3377d1cf, v20
	v_fmac_f32_e32 v24, 0x3f317217, v20
	v_cmp_lt_f32_e64 s[0:1], |v20|, s86
	s_nop 1
	v_cndmask_b32_e64 v20, v20, v24, s[0:1]
	v_cndmask_b32_e32 v24, 0, v224, vcc
	v_sub_f32_e32 v20, v20, v24
	v_fma_f32 v24, v33, v195, v135
	v_cmp_gt_f32_e32 vcc, s16, v24
	v_sub_f32_e32 v33, 1.0, v33
	v_mul_f32_e32 v33, v33, v195
	v_cndmask_b32_e64 v34, 0, 32, vcc
	v_ldexp_f32 v24, v24, v34
	v_log_f32_e32 v24, v24
	s_nop 0
	v_mul_f32_e32 v34, 0x3f317217, v24
	v_fma_f32 v34, v24, s17, -v34
	v_fmac_f32_e32 v34, 0x3377d1cf, v24
	v_fmac_f32_e32 v34, 0x3f317217, v24
	v_cmp_lt_f32_e64 s[0:1], |v24|, s86
	s_nop 1
	v_cndmask_b32_e64 v24, v24, v34, s[0:1]
	v_cndmask_b32_e32 v34, 0, v224, vcc
	v_sub_f32_e32 v24, v24, v34
	v_rcp_f32_e32 v34, v25
	s_nop 0
	v_fma_f32 v21, v34, v123, v139
	v_cmp_gt_f32_e32 vcc, s16, v21
	v_sub_f32_e32 v34, 1.0, v34
	v_mul_f32_e32 v34, v34, v123
	v_cndmask_b32_e64 v25, 0, 32, vcc
	v_ldexp_f32 v21, v21, v25
	v_log_f32_e32 v21, v21
	s_nop 0
	v_mul_f32_e32 v25, 0x3f317217, v21
	v_fma_f32 v25, v21, s17, -v25
	v_fmac_f32_e32 v25, 0x3377d1cf, v21
	v_fmac_f32_e32 v25, 0x3f317217, v21
	v_cmp_lt_f32_e64 s[0:1], |v21|, s86
	s_nop 1
	v_cndmask_b32_e64 v21, v21, v25, s[0:1]
	v_cndmask_b32_e32 v25, 0, v224, vcc
	v_sub_f32_e32 v21, v21, v25
	v_fma_f32 v25, v35, v167, v131
	v_cmp_gt_f32_e32 vcc, s16, v25
	v_sub_f32_e32 v35, 1.0, v35
	v_mul_f32_e32 v35, v35, v167
	v_cndmask_b32_e64 v38, 0, 32, vcc
	v_ldexp_f32 v25, v25, v38
	v_log_f32_e32 v25, v25
	s_nop 0
	v_mul_f32_e32 v38, 0x3f317217, v25
	v_fma_f32 v38, v25, s17, -v38
	v_fmac_f32_e32 v38, 0x3377d1cf, v25
	v_fmac_f32_e32 v38, 0x3f317217, v25
	v_cmp_lt_f32_e64 s[0:1], |v25|, s86
	s_nop 1
	v_cndmask_b32_e64 v25, v25, v38, s[0:1]
	v_cndmask_b32_e32 v38, 0, v224, vcc
	v_sub_f32_e32 v25, v25, v38
	global_store_dwordx4 v[36:37], v[18:21], off offset:-3584 nt
	global_store_dwordx4 v[36:37], v[22:25], off offset:-3568 nt
	s_nop 0
	v_cvt_pk_bf16_f32 v18, v28, v30
	v_cvt_pk_bf16_f32 v19, v32, v34
	v_cvt_pk_bf16_f32 v20, v29, v31
	v_cvt_pk_bf16_f32 v21, v33, v35
	global_store_dwordx4 v[26:27], v[18:21], off offset:256 nt
	v_rcp_f32_e32 v22, v10
	v_rcp_f32_e32 v24, v11
	v_add_u32_e32 v18, 0xb0, v164
	v_ashrrev_i32_e32 v19, 31, v18
	v_lshlrev_b64 v[20:21], 12, v[18:19]
	v_rcp_f32_e32 v19, v14
	v_fmac_f32_e32 v185, v22, v207
	v_fmac_f32_e32 v183, v24, v205
	v_rcp_f32_e32 v26, v12
	v_fmac_f32_e32 v171, v19, v193
	v_cmp_gt_f32_e32 vcc, s16, v171
	v_rcp_f32_e32 v28, v13
	v_fmac_f32_e32 v181, v26, v203
	v_cndmask_b32_e64 v10, 0, 32, vcc
	v_ldexp_f32 v10, v171, v10
	v_log_f32_e32 v10, v10
	v_fmac_f32_e32 v179, v28, v201
	v_lshl_add_u64 v[20:21], s[12:13], 0, v[20:21]
	v_lshl_add_u64 v[20:21], v[20:21], 0, v[168:169]
	v_mul_f32_e32 v14, 0x3f317217, v10
	v_fma_f32 v14, v10, s17, -v14
	v_fmac_f32_e32 v14, 0x3377d1cf, v10
	v_fmac_f32_e32 v14, 0x3f317217, v10
	v_cmp_lt_f32_e64 s[0:1], |v10|, s86
	v_sub_f32_e32 v19, 1.0, v19
	v_mul_f32_e32 v19, v19, v193
	v_cndmask_b32_e64 v10, v10, v14, s[0:1]
	v_cndmask_b32_e32 v14, 0, v224, vcc
	v_cmp_gt_f32_e32 vcc, s16, v185
	v_sub_f32_e32 v10, v10, v14
	v_sub_f32_e32 v22, 1.0, v22
	v_cndmask_b32_e64 v14, 0, 32, vcc
	v_ldexp_f32 v14, v185, v14
	v_log_f32_e32 v14, v14
	v_sub_f32_e32 v24, 1.0, v24
	v_sub_f32_e32 v26, 1.0, v26
	v_sub_f32_e32 v28, 1.0, v28
	v_mul_f32_e32 v23, 0x3f317217, v14
	v_fma_f32 v23, v14, s17, -v23
	v_fmac_f32_e32 v23, 0x3377d1cf, v14
	v_fmac_f32_e32 v23, 0x3f317217, v14
	v_cmp_lt_f32_e64 s[0:1], |v14|, s86
	v_mul_f32_e32 v22, v22, v207
	v_mul_f32_e32 v24, v24, v205
	v_cndmask_b32_e64 v14, v14, v23, s[0:1]
	v_cndmask_b32_e32 v23, 0, v224, vcc
	v_sub_f32_e32 v14, v14, v23
	v_rcp_f32_e32 v23, v15
	v_mul_f32_e32 v26, v26, v203
	v_mul_f32_e32 v28, v28, v201
	v_fmac_f32_e32 v173, v23, v191
	v_cmp_gt_f32_e32 vcc, s16, v173
	v_sub_f32_e32 v23, 1.0, v23
	v_mul_f32_e32 v23, v23, v191
	v_cndmask_b32_e64 v11, 0, 32, vcc
	v_ldexp_f32 v11, v173, v11
	v_log_f32_e32 v11, v11
	s_nop 0
	v_mul_f32_e32 v15, 0x3f317217, v11
	v_fma_f32 v15, v11, s17, -v15
	v_fmac_f32_e32 v15, 0x3377d1cf, v11
	v_fmac_f32_e32 v15, 0x3f317217, v11
	v_cmp_lt_f32_e64 s[0:1], |v11|, s86
	s_nop 1
	v_cndmask_b32_e64 v11, v11, v15, s[0:1]
	v_cndmask_b32_e32 v15, 0, v224, vcc
	v_cmp_gt_f32_e32 vcc, s16, v183
	v_sub_f32_e32 v11, v11, v15
	s_nop 0
	v_cndmask_b32_e64 v15, 0, 32, vcc
	v_ldexp_f32 v15, v183, v15
	v_log_f32_e32 v15, v15
	s_nop 0
	v_mul_f32_e32 v25, 0x3f317217, v15
	v_fma_f32 v25, v15, s17, -v25
	v_fmac_f32_e32 v25, 0x3377d1cf, v15
	v_fmac_f32_e32 v25, 0x3f317217, v15
	v_cmp_lt_f32_e64 s[0:1], |v15|, s86
	s_nop 1
	v_cndmask_b32_e64 v15, v15, v25, s[0:1]
	v_cndmask_b32_e32 v25, 0, v224, vcc
	v_sub_f32_e32 v15, v15, v25
	v_rcp_f32_e32 v25, v16
	s_nop 0
	v_fmac_f32_e32 v175, v25, v137
	v_cmp_gt_f32_e32 vcc, s16, v175
	v_sub_f32_e32 v25, 1.0, v25
	v_mul_f32_e32 v25, v25, v137
	v_cndmask_b32_e64 v12, 0, 32, vcc
	v_ldexp_f32 v12, v175, v12
	v_log_f32_e32 v12, v12
	s_nop 0
	v_mul_f32_e32 v16, 0x3f317217, v12
	v_fma_f32 v16, v12, s17, -v16
	v_fmac_f32_e32 v16, 0x3377d1cf, v12
	v_fmac_f32_e32 v16, 0x3f317217, v12
	v_cmp_lt_f32_e64 s[0:1], |v12|, s86
	s_nop 1
	v_cndmask_b32_e64 v12, v12, v16, s[0:1]
	v_cndmask_b32_e32 v16, 0, v224, vcc
	v_cmp_gt_f32_e32 vcc, s16, v181
	v_sub_f32_e32 v12, v12, v16
	s_nop 0
	v_cndmask_b32_e64 v16, 0, 32, vcc
	v_ldexp_f32 v16, v181, v16
	v_log_f32_e32 v16, v16
	s_nop 0
	v_mul_f32_e32 v27, 0x3f317217, v16
	v_fma_f32 v27, v16, s17, -v27
	v_fmac_f32_e32 v27, 0x3377d1cf, v16
	v_fmac_f32_e32 v27, 0x3f317217, v16
	v_cmp_lt_f32_e64 s[0:1], |v16|, s86
	s_nop 1
	v_cndmask_b32_e64 v16, v16, v27, s[0:1]
	v_cndmask_b32_e32 v27, 0, v224, vcc
	v_sub_f32_e32 v16, v16, v27
	v_rcp_f32_e32 v27, v17
	s_nop 0
	v_fmac_f32_e32 v177, v27, v133
	v_cmp_gt_f32_e32 vcc, s16, v177
	v_sub_f32_e32 v27, 1.0, v27
	v_mul_f32_e32 v27, v27, v133
	v_cndmask_b32_e64 v13, 0, 32, vcc
	v_ldexp_f32 v13, v177, v13
	v_log_f32_e32 v13, v13
	s_nop 0
	v_mul_f32_e32 v17, 0x3f317217, v13
	v_fma_f32 v17, v13, s17, -v17
	v_fmac_f32_e32 v17, 0x3377d1cf, v13
	v_fmac_f32_e32 v17, 0x3f317217, v13
	v_cmp_lt_f32_e64 s[0:1], |v13|, s86
	s_nop 1
	v_cndmask_b32_e64 v13, v13, v17, s[0:1]
	v_cndmask_b32_e32 v17, 0, v224, vcc
	v_cmp_gt_f32_e32 vcc, s16, v179
	v_sub_f32_e32 v13, v13, v17
	s_nop 0
	v_cndmask_b32_e64 v17, 0, 32, vcc
	v_ldexp_f32 v17, v179, v17
	v_log_f32_e32 v17, v17
	s_nop 0
	v_mul_f32_e32 v29, 0x3f317217, v17
	v_fma_f32 v29, v17, s17, -v29
	v_fmac_f32_e32 v29, 0x3377d1cf, v17
	v_fmac_f32_e32 v29, 0x3f317217, v17
	v_cmp_lt_f32_e64 s[0:1], |v17|, s86
	s_nop 1
	v_cndmask_b32_e64 v17, v17, v29, s[0:1]
	v_cndmask_b32_e32 v29, 0, v224, vcc
	v_sub_f32_e32 v17, v17, v29
	global_store_dwordx4 v[20:21], v[10:13], off offset:-4096 nt
	global_store_dwordx4 v[20:21], v[14:17], off offset:-4080 nt
	s_nop 0
	v_mad_i64_i32 v[10:11], s[0:1], v18, s8, v[208:209]
	v_cvt_pk_bf16_f32 v12, v19, v23
	v_lshl_add_u64 v[10:11], v[10:11], 0, v[210:211]
	v_cvt_pk_bf16_f32 v13, v25, v27
	v_cvt_pk_bf16_f32 v14, v22, v24
	v_cvt_pk_bf16_f32 v15, v26, v28
	global_store_dwordx4 v[10:11], v[12:15], off nt
	v_rcp_f32_e32 v17, v4
	v_rcp_f32_e32 v19, v5
	v_rcp_f32_e32 v12, v6
	v_rcp_f32_e32 v13, v2
	v_rcp_f32_e32 v15, v3
	v_fmac_f32_e32 v135, v17, v195
	v_fmac_f32_e32 v189, v12, v129
	v_cmp_gt_f32_e32 vcc, s16, v189
	v_fmac_f32_e32 v145, v13, v199
	v_fmac_f32_e32 v141, v15, v197
	v_cndmask_b32_e64 v2, 0, 32, vcc
	v_ldexp_f32 v2, v189, v2
	v_log_f32_e32 v2, v2
	v_fmac_f32_e32 v131, v19, v167
	v_sub_f32_e32 v12, 1.0, v12
	v_sub_f32_e32 v13, 1.0, v13
	v_mul_f32_e32 v6, 0x3f317217, v2
	v_fma_f32 v6, v2, s17, -v6
	v_fmac_f32_e32 v6, 0x3377d1cf, v2
	v_fmac_f32_e32 v6, 0x3f317217, v2
	v_cmp_lt_f32_e64 s[0:1], |v2|, s86
	v_sub_f32_e32 v15, 1.0, v15
	v_sub_f32_e32 v17, 1.0, v17
	v_cndmask_b32_e64 v2, v2, v6, s[0:1]
	v_cndmask_b32_e32 v6, 0, v224, vcc
	v_cmp_gt_f32_e32 vcc, s16, v145
	v_sub_f32_e32 v2, v2, v6
	v_sub_f32_e32 v19, 1.0, v19
	v_cndmask_b32_e64 v6, 0, 32, vcc
	v_ldexp_f32 v6, v145, v6
	v_log_f32_e32 v6, v6
	v_mul_f32_e32 v12, v12, v129
	v_mul_f32_e32 v13, v13, v199
	v_mul_f32_e32 v15, v15, v197
	v_mul_f32_e32 v14, 0x3f317217, v6
	v_fma_f32 v14, v6, s17, -v14
	v_fmac_f32_e32 v14, 0x3377d1cf, v6
	v_fmac_f32_e32 v14, 0x3f317217, v6
	v_cmp_lt_f32_e64 s[0:1], |v6|, s86
	v_mul_f32_e32 v17, v17, v195
	v_mul_f32_e32 v19, v19, v167
	v_cndmask_b32_e64 v6, v6, v14, s[0:1]
	v_cndmask_b32_e32 v14, 0, v224, vcc
	v_sub_f32_e32 v6, v6, v14
	v_rcp_f32_e32 v14, v7
	s_nop 0
	v_fmac_f32_e32 v187, v14, v127
	v_cmp_gt_f32_e32 vcc, s16, v187
	v_sub_f32_e32 v14, 1.0, v14
	v_mul_f32_e32 v14, v14, v127
	v_cndmask_b32_e64 v3, 0, 32, vcc
	v_ldexp_f32 v3, v187, v3
	v_log_f32_e32 v3, v3
	s_nop 0
	v_mul_f32_e32 v7, 0x3f317217, v3
	v_fma_f32 v7, v3, s17, -v7
	v_fmac_f32_e32 v7, 0x3377d1cf, v3
	v_fmac_f32_e32 v7, 0x3f317217, v3
	v_cmp_lt_f32_e64 s[0:1], |v3|, s86
	s_nop 1
	v_cndmask_b32_e64 v3, v3, v7, s[0:1]
	v_cndmask_b32_e32 v7, 0, v224, vcc
	v_cmp_gt_f32_e32 vcc, s16, v141
	v_sub_f32_e32 v3, v3, v7
	s_nop 0
	v_cndmask_b32_e64 v7, 0, 32, vcc
	v_ldexp_f32 v7, v141, v7
	v_log_f32_e32 v7, v7
	s_nop 0
	v_mul_f32_e32 v16, 0x3f317217, v7
	v_fma_f32 v16, v7, s17, -v16
	v_fmac_f32_e32 v16, 0x3377d1cf, v7
	v_fmac_f32_e32 v16, 0x3f317217, v7
	v_cmp_lt_f32_e64 s[0:1], |v7|, s86
	s_nop 1
	v_cndmask_b32_e64 v7, v7, v16, s[0:1]
	v_cndmask_b32_e32 v16, 0, v224, vcc
	v_sub_f32_e32 v7, v7, v16
	v_rcp_f32_e32 v16, v8
	s_nop 0
	v_fmac_f32_e32 v143, v16, v125
	v_cmp_gt_f32_e32 vcc, s16, v143
	v_sub_f32_e32 v16, 1.0, v16
	v_mul_f32_e32 v16, v16, v125
	v_cndmask_b32_e64 v4, 0, 32, vcc
	v_ldexp_f32 v4, v143, v4
	v_log_f32_e32 v4, v4
	s_nop 0
	v_mul_f32_e32 v8, 0x3f317217, v4
	v_fma_f32 v8, v4, s17, -v8
	v_fmac_f32_e32 v8, 0x3377d1cf, v4
	v_fmac_f32_e32 v8, 0x3f317217, v4
	v_cmp_lt_f32_e64 s[0:1], |v4|, s86
	s_nop 1
	v_cndmask_b32_e64 v4, v4, v8, s[0:1]
	v_cndmask_b32_e32 v8, 0, v224, vcc
	v_cmp_gt_f32_e32 vcc, s16, v135
	v_sub_f32_e32 v4, v4, v8
	s_nop 0
	v_cndmask_b32_e64 v8, 0, 32, vcc
	v_ldexp_f32 v8, v135, v8
	v_log_f32_e32 v8, v8
	s_nop 0
	v_mul_f32_e32 v18, 0x3f317217, v8
	v_fma_f32 v18, v8, s17, -v18
	v_fmac_f32_e32 v18, 0x3377d1cf, v8
	v_fmac_f32_e32 v18, 0x3f317217, v8
	v_cmp_lt_f32_e64 s[0:1], |v8|, s86
	s_nop 1
	v_cndmask_b32_e64 v8, v8, v18, s[0:1]
	v_cndmask_b32_e32 v18, 0, v224, vcc
	v_sub_f32_e32 v8, v8, v18
	v_rcp_f32_e32 v18, v9
	s_nop 0
	v_fmac_f32_e32 v139, v18, v123
	v_cmp_gt_f32_e32 vcc, s16, v139
	v_sub_f32_e32 v18, 1.0, v18
	v_mul_f32_e32 v18, v18, v123
	v_cndmask_b32_e64 v5, 0, 32, vcc
	v_ldexp_f32 v5, v139, v5
	v_log_f32_e32 v5, v5
	s_nop 0
	v_mul_f32_e32 v9, 0x3f317217, v5
	v_fma_f32 v9, v5, s17, -v9
	v_fmac_f32_e32 v9, 0x3377d1cf, v5
	v_fmac_f32_e32 v9, 0x3f317217, v5
	v_cmp_lt_f32_e64 s[0:1], |v5|, s86
	s_nop 1
	v_cndmask_b32_e64 v5, v5, v9, s[0:1]
	v_cndmask_b32_e32 v9, 0, v224, vcc
	v_cmp_gt_f32_e32 vcc, s16, v131
	v_sub_f32_e32 v5, v5, v9
	s_nop 0
	v_cndmask_b32_e64 v9, 0, 32, vcc
	v_ldexp_f32 v9, v131, v9
	v_log_f32_e32 v9, v9
	s_nop 0
	v_mul_f32_e32 v22, 0x3f317217, v9
	v_fma_f32 v22, v9, s17, -v22
	v_fmac_f32_e32 v22, 0x3377d1cf, v9
	v_fmac_f32_e32 v22, 0x3f317217, v9
	v_cmp_lt_f32_e64 s[0:1], |v9|, s86
	s_nop 1
	v_cndmask_b32_e64 v9, v9, v22, s[0:1]
	v_cndmask_b32_e32 v22, 0, v224, vcc
	v_sub_f32_e32 v9, v9, v22
	global_store_dwordx4 v[20:21], v[2:5], off offset:-3584 nt
	global_store_dwordx4 v[20:21], v[6:9], off offset:-3568 nt
	s_nop 0
	v_cvt_pk_bf16_f32 v2, v12, v14
	v_cvt_pk_bf16_f32 v3, v16, v18
	v_cvt_pk_bf16_f32 v4, v13, v15
	v_cvt_pk_bf16_f32 v5, v17, v19
	global_store_dwordx4 v[10:11], v[2:5], off offset:256 nt
	s_andn2_b64 vcc, exec, s[2:3]
	s_mov_b64 s[0:1], -1
	s_cbranch_vccnz .LBB0_142
